# code placement: inner waits/prio flips removed inside clusters and s_nop pads in load segments so that every K-loop MFMA is 8-byte aligned; P7 loop-final cluster with baseline barrier
# baseline (speedup 1.0000x reference)
; #define PG8_STAGE(bufoff, gbase, voff) do { _Pragma("unroll") for (int _i = 0; _i < 2; ++_i) \
;         asm volatile("s_mov_b32 m0, %2\n\ts_nop 0\n\tglobal_load_lds_dwordx4 %0, %1" :: "v"((voff)[_i]), "s"((const char*)(gbase)), "s"(ldsbase + (unsigned)(bufoff) + ldsw + (unsigned)_i * 8192u) : "memory", "m0"); } while (0)
; #define PG8_LDA(dst, b, h) do { _Pragma("unroll") for (int m = 0; m < 4; ++m) _Pragma("unroll") for (int k = 0; k < 2; ++k) dst[m][k] = *(const PG8_LAS bf16x8*)(lds + PG8_SA(b, h) + aoff + m * 2048 + k * 1024); } while (0)
; #define PG8_LDB(dst, b, h) do { _Pragma("unroll") for (int n = 0; n < 2; ++n) _Pragma("unroll") for (int k = 0; k < 2; ++k) dst[n][k] = *(const PG8_LAS bf16x8*)(lds + PG8_SB(b, h) + boff + n * 2048 + k * 1024); } while (0)
; #define PG8_MMA(ai, bj, At, Bt) do { __builtin_amdgcn_s_setprio(1); _Pragma("unroll") for (int m = 0; m < 4; ++m) _Pragma("unroll") for (int n = 0; n < 2; ++n) _Pragma("unroll") for (int k = 0; k < 2; ++k) \
;         acc[ai][bj][m][n] = __builtin_amdgcn_mfma_f32_16x16x32_bf16(Bt[n][k], At[m][k], acc[ai][bj][m][n], 0, 0, 0); __builtin_amdgcn_s_setprio(0); } while (0)
; template <class Epi, class Sched, bool ALIGN_EPI = false, bool SP2 = false>
; __device__ __forceinline__ void gemm_phase(PG8_LAS unsigned char* lds, const Gemm g, const Sched& S, const Epi& E) {
;     ...
;             PG8_LDB(B0, 0, 0); PG8_LDB(B1, 0, 1); PG8_SCHED; PG8_LDA(At, 0, 0); PG8_STAGE(PG8_SA(1, 1), a1 + hstep, voffA);
;             PG8_WAIT_V(8); PG8_WAIT_L(0); PG8_BAR; PG8_MMA(0, 0, At, B0); PG8_MMA(0, 1, At, B1); PG8_BAR; PG8_SCHED;
;             PG8_LDA(At, 0, 1); PG8_STAGE(PG8_SB(0, 0), b2, voffB); PG8_STAGE(PG8_SB(0, 1), b2 + hstep, voffB); PG8_STAGE(PG8_SA(0, 0), a2, voffA);
;             PG8_WAIT_V(8); PG8_WAIT_L(0); PG8_BAR; PG8_MMA(1, 0, At, B0); PG8_MMA(1, 1, At, B1); PG8_BAR; PG8_SCHED;
;             PG8_LDB(B0, 1, 0); PG8_LDB(B1, 1, 1); PG8_SCHED; PG8_LDA(At, 1, 0); PG8_STAGE(PG8_SA(0, 1), a2 + hstep, voffA);
;             PG8_WAIT_V(8); PG8_WAIT_L(0); PG8_BAR; PG8_MMA(0, 0, At, B0); PG8_MMA(0, 1, At, B1); PG8_BAR; PG8_SCHED;
;             PG8_LDA(At, 1, 1); PG8_STAGE(PG8_SB(1, 0), b3, voffB); PG8_STAGE(PG8_SB(1, 1), b3 + hstep, voffB); PG8_STAGE(PG8_SA(1, 0), a3, voffA);
;             PG8_WAIT_V(8); PG8_WAIT_L(0); PG8_BAR; PG8_MMA(1, 0, At, B0); PG8_MMA(1, 1, At, B1); PG8_BAR; PG8_SCHED;
.LBB0_234:
	ds_read_b128 v[134:137], v145
	ds_read_b128 v[152:155], v145 offset:1024
	ds_read_b128 v[156:159], v145 offset:2048
	ds_read_b128 v[160:163], v145 offset:3072
	ds_read_b128 v[164:167], v146
	ds_read_b128 v[168:171], v146 offset:1024
	ds_read_b128 v[172:175], v146 offset:2048
	ds_read_b128 v[176:179], v146 offset:3072
	s_cmpk_eq_i32 s57, 0xa8
	s_cselect_b32 s76, s4, s53
	s_cselect_b32 s77, s5, s54
	s_cselect_b32 s66, s46, s55
	s_cselect_b32 s67, s47, s56
	s_add_u32 s62, s76, 0x80
	s_addc_u32 s63, s77, 0
	ds_read_b128 v[180:183], v147
	ds_read_b128 v[184:187], v147 offset:1024
	ds_read_b128 v[188:191], v147 offset:2048
	ds_read_b128 v[192:195], v147 offset:3072
	ds_read_b128 v[196:199], v147 offset:4096
	ds_read_b128 v[200:203], v147 offset:5120
	ds_read_b128 v[204:207], v147 offset:6144
	ds_read_b128 v[208:211], v147 offset:7168
	s_mov_b32 m0, s94
	s_nop 0
	global_load_lds_dwordx4 v1, s[50:51]
	s_nop 0
	s_mov_b32 m0, s95
	s_nop 0
	global_load_lds_dwordx4 v141, s[50:51]
	s_nop 0
	s_waitcnt vmcnt(8)
	s_waitcnt lgkmcnt(0)
	s_barrier
	s_setprio 1
	s_waitcnt lgkmcnt(7)
	v_mfma_f32_16x16x32_bf16 v[126:129], v[134:137], v[180:183], v[126:129]
	v_mfma_f32_16x16x32_bf16 v[126:129], v[152:155], v[184:187], v[126:129]
	v_mfma_f32_16x16x32_bf16 v[122:125], v[160:163], v[184:187], v[122:125]
	v_mfma_f32_16x16x32_bf16 v[122:125], v[156:159], v[180:183], v[122:125]
	v_mfma_f32_16x16x32_bf16 v[118:121], v[164:167], v[180:183], v[118:121]
	v_mfma_f32_16x16x32_bf16 v[118:121], v[168:171], v[184:187], v[118:121]
	v_mfma_f32_16x16x32_bf16 v[114:117], v[176:179], v[184:187], v[114:117]
	v_mfma_f32_16x16x32_bf16 v[114:117], v[172:175], v[180:183], v[114:117]
	v_mfma_f32_16x16x32_bf16 v[98:101], v[172:175], v[188:191], v[98:101]
	v_mfma_f32_16x16x32_bf16 v[98:101], v[176:179], v[192:195], v[98:101]
	v_mfma_f32_16x16x32_bf16 v[102:105], v[168:171], v[192:195], v[102:105]
	v_mfma_f32_16x16x32_bf16 v[102:105], v[164:167], v[188:191], v[102:105]
	v_mfma_f32_16x16x32_bf16 v[106:109], v[156:159], v[188:191], v[106:109]
	v_mfma_f32_16x16x32_bf16 v[106:109], v[160:163], v[192:195], v[106:109]
	v_mfma_f32_16x16x32_bf16 v[110:113], v[152:155], v[192:195], v[110:113]
	v_mfma_f32_16x16x32_bf16 v[110:113], v[134:137], v[188:191], v[110:113]
	v_mfma_f32_16x16x32_bf16 v[94:97], v[134:137], v[196:199], v[94:97]
	v_mfma_f32_16x16x32_bf16 v[94:97], v[152:155], v[200:203], v[94:97]
	v_mfma_f32_16x16x32_bf16 v[90:93], v[160:163], v[200:203], v[90:93]
	v_mfma_f32_16x16x32_bf16 v[90:93], v[156:159], v[196:199], v[90:93]
	v_mfma_f32_16x16x32_bf16 v[86:89], v[164:167], v[196:199], v[86:89]
	v_mfma_f32_16x16x32_bf16 v[86:89], v[168:171], v[200:203], v[86:89]
	v_mfma_f32_16x16x32_bf16 v[82:85], v[176:179], v[200:203], v[82:85]
	v_mfma_f32_16x16x32_bf16 v[82:85], v[172:175], v[196:199], v[82:85]
	v_mfma_f32_16x16x32_bf16 v[66:69], v[172:175], v[204:207], v[66:69]
	v_mfma_f32_16x16x32_bf16 v[66:69], v[176:179], v[208:211], v[66:69]
	v_mfma_f32_16x16x32_bf16 v[70:73], v[168:171], v[208:211], v[70:73]
	v_mfma_f32_16x16x32_bf16 v[70:73], v[164:167], v[204:207], v[70:73]
	v_mfma_f32_16x16x32_bf16 v[74:77], v[156:159], v[204:207], v[74:77]
	v_mfma_f32_16x16x32_bf16 v[74:77], v[160:163], v[208:211], v[74:77]
	v_mfma_f32_16x16x32_bf16 v[78:81], v[152:155], v[208:211], v[78:81]
	s_setprio 2
	s_barrier
	v_mfma_f32_16x16x32_bf16 v[78:81], v[134:137], v[204:207], v[78:81]
	s_setprio 0
	ds_read_b128 v[180:183], v147 offset:16384
	ds_read_b128 v[184:187], v147 offset:17408
	ds_read_b128 v[188:191], v147 offset:18432
	ds_read_b128 v[192:195], v147 offset:19456
	ds_read_b128 v[196:199], v147 offset:20480
	ds_read_b128 v[200:203], v147 offset:21504
	ds_read_b128 v[252:255], v147 offset:22528
	ds_read_b128 v[208:211], v147 offset:23552
	s_mov_b32 m0, s64
	s_nop 0
	global_load_lds_dwordx4 v140, s[66:67]
	s_add_u32 s58, s66, 0x2b0000
	s_mov_b32 m0, s65
	s_nop 0
	global_load_lds_dwordx4 v142, s[66:67]
	s_addc_u32 s59, s67, 0
	s_mov_b32 m0, s82
	s_nop 0
	global_load_lds_dwordx4 v140, s[58:59]
	s_nop 0
	s_mov_b32 m0, s83
	s_nop 0
	global_load_lds_dwordx4 v142, s[58:59]
	s_nop 0
	s_mov_b32 m0, s35
	s_nop 0
	global_load_lds_dwordx4 v1, s[76:77]
	s_nop 0
	s_mov_b32 m0, s84
	s_nop 0
	global_load_lds_dwordx4 v141, s[76:77]
	s_waitcnt vmcnt(8)
	s_waitcnt lgkmcnt(0)
	s_barrier
	s_setprio 1
	s_waitcnt lgkmcnt(7)
	v_mfma_f32_16x16x32_bf16 v[62:65], v[134:137], v[180:183], v[62:65]
	v_mfma_f32_16x16x32_bf16 v[62:65], v[152:155], v[184:187], v[62:65]
	v_mfma_f32_16x16x32_bf16 v[58:61], v[160:163], v[184:187], v[58:61]
	v_mfma_f32_16x16x32_bf16 v[58:61], v[156:159], v[180:183], v[58:61]
	v_mfma_f32_16x16x32_bf16 v[54:57], v[164:167], v[180:183], v[54:57]
	v_mfma_f32_16x16x32_bf16 v[54:57], v[168:171], v[184:187], v[54:57]
	v_mfma_f32_16x16x32_bf16 v[50:53], v[176:179], v[184:187], v[50:53]
	v_mfma_f32_16x16x32_bf16 v[50:53], v[172:175], v[180:183], v[50:53]
	v_mfma_f32_16x16x32_bf16 v[34:37], v[172:175], v[188:191], v[34:37]
	v_mfma_f32_16x16x32_bf16 v[34:37], v[176:179], v[192:195], v[34:37]
	v_mfma_f32_16x16x32_bf16 v[38:41], v[168:171], v[192:195], v[38:41]
	v_mfma_f32_16x16x32_bf16 v[38:41], v[164:167], v[188:191], v[38:41]
	v_mfma_f32_16x16x32_bf16 v[42:45], v[156:159], v[188:191], v[42:45]
	v_mfma_f32_16x16x32_bf16 v[42:45], v[160:163], v[192:195], v[42:45]
	v_mfma_f32_16x16x32_bf16 v[46:49], v[152:155], v[192:195], v[46:49]
	v_mfma_f32_16x16x32_bf16 v[46:49], v[134:137], v[188:191], v[46:49]
	v_mfma_f32_16x16x32_bf16 v[30:33], v[134:137], v[196:199], v[30:33]
	v_mfma_f32_16x16x32_bf16 v[30:33], v[152:155], v[200:203], v[30:33]
	v_mfma_f32_16x16x32_bf16 v[26:29], v[160:163], v[200:203], v[26:29]
	v_mfma_f32_16x16x32_bf16 v[26:29], v[156:159], v[196:199], v[26:29]
	v_mfma_f32_16x16x32_bf16 v[22:25], v[164:167], v[196:199], v[22:25]
	v_mfma_f32_16x16x32_bf16 v[22:25], v[168:171], v[200:203], v[22:25]
	v_mfma_f32_16x16x32_bf16 v[18:21], v[176:179], v[200:203], v[18:21]
	v_mfma_f32_16x16x32_bf16 v[18:21], v[172:175], v[196:199], v[18:21]
	v_mfma_f32_16x16x32_bf16 v[2:5], v[172:175], v[252:255], v[2:5]
	v_mfma_f32_16x16x32_bf16 v[2:5], v[176:179], v[208:211], v[2:5]
	v_mfma_f32_16x16x32_bf16 v[6:9], v[168:171], v[208:211], v[6:9]
	v_mfma_f32_16x16x32_bf16 v[6:9], v[164:167], v[252:255], v[6:9]
	v_mfma_f32_16x16x32_bf16 v[10:13], v[156:159], v[252:255], v[10:13]
	v_mfma_f32_16x16x32_bf16 v[10:13], v[160:163], v[208:211], v[10:13]
	v_mfma_f32_16x16x32_bf16 v[14:17], v[152:155], v[208:211], v[14:17]
	s_setprio 2
	s_barrier
; #define PG8_STAGE(bufoff, gbase, voff) do { _Pragma("unroll") for (int _i = 0; _i < 2; ++_i) \
;         asm volatile("s_mov_b32 m0, %2\n\ts_nop 0\n\tglobal_load_lds_dwordx4 %0, %1" :: "v"((voff)[_i]), "s"((const char*)(gbase)), "s"(ldsbase + (unsigned)(bufoff) + ldsw + (unsigned)_i * 8192u) : "memory", "m0"); } while (0)
; #define PG8_LDA(dst, b, h) do { _Pragma("unroll") for (int m = 0; m < 4; ++m) _Pragma("unroll") for (int k = 0; k < 2; ++k) dst[m][k] = *(const PG8_LAS bf16x8*)(lds + PG8_SA(b, h) + aoff + m * 2048 + k * 1024); } while (0)
; #define PG8_LDB(dst, b, h) do { _Pragma("unroll") for (int n = 0; n < 2; ++n) _Pragma("unroll") for (int k = 0; k < 2; ++k) dst[n][k] = *(const PG8_LAS bf16x8*)(lds + PG8_SB(b, h) + boff + n * 2048 + k * 1024); } while (0)
; #define PG8_MMA(ai, bj, At, Bt) do { __builtin_amdgcn_s_setprio(1); _Pragma("unroll") for (int m = 0; m < 4; ++m) _Pragma("unroll") for (int n = 0; n < 2; ++n) _Pragma("unroll") for (int k = 0; k < 2; ++k) \
;         acc[ai][bj][m][n] = __builtin_amdgcn_mfma_f32_16x16x32_bf16(Bt[n][k], At[m][k], acc[ai][bj][m][n], 0, 0, 0); __builtin_amdgcn_s_setprio(0); } while (0)
; #define PG8_WAIT_V(n) asm volatile("s_waitcnt vmcnt(" #n ")" ::: "memory")
; #define PG8_WAIT_L(n) asm volatile("s_waitcnt lgkmcnt(" #n ")" ::: "memory")
; #define PG8_BAR __builtin_amdgcn_s_barrier()
; #define PG8_SCHED __builtin_amdgcn_sched_barrier(0)
; template <class Epi, class Sched, bool ALIGN_EPI = false, bool SP2 = false>
; __device__ __forceinline__ void gemm_phase(PG8_LAS unsigned char* lds, const Gemm g, const Sched& S, const Epi& E) {
;     ...
;         for (int t = 0; t < nt; t += 2) {
;             const bool last = (t == nt - 2);
;     ...
;             PG8_LDB(B0, 1, 0); PG8_LDB(B1, 1, 1); PG8_SCHED; PG8_LDA(At, 1, 0); PG8_STAGE(PG8_SA(0, 1), a2 + hstep, voffA);
;             PG8_WAIT_V(8); PG8_WAIT_L(0); PG8_BAR; PG8_MMA(0, 0, At, B0); PG8_MMA(0, 1, At, B1); PG8_BAR; PG8_SCHED;
;             PG8_LDA(At, 1, 1); PG8_STAGE(PG8_SB(1, 0), b3, voffB); PG8_STAGE(PG8_SB(1, 1), b3 + hstep, voffB); PG8_STAGE(PG8_SA(1, 0), a3, voffA);
;             PG8_WAIT_V(8); PG8_WAIT_L(0); PG8_BAR; PG8_MMA(1, 0, At, B0); PG8_MMA(1, 1, At, B1); PG8_BAR; PG8_SCHED;
	v_mfma_f32_16x16x32_bf16 v[14:17], v[134:137], v[252:255], v[14:17]
	s_setprio 0
	ds_read_b128 v[248:251], v148
	ds_read_b128 v[152:155], v148 offset:1024
	ds_read_b128 v[156:159], v148 offset:2048
	ds_read_b128 v[160:163], v148 offset:3072
	ds_read_b128 v[164:167], v149
	ds_read_b128 v[168:171], v149 offset:1024
	ds_read_b128 v[172:175], v149 offset:2048
	ds_read_b128 v[176:179], v149 offset:3072
	ds_read_b128 v[180:183], v147 offset:32768
	ds_read_b128 v[184:187], v147 offset:33792
	ds_read_b128 v[188:191], v147 offset:34816
	ds_read_b128 v[192:195], v147 offset:35840
	ds_read_b128 v[196:199], v147 offset:36864
	ds_read_b128 v[200:203], v147 offset:37888
	ds_read_b128 v[204:207], v147 offset:38912
	ds_read_b128 v[208:211], v147 offset:39936
	s_add_u32 s58, s76, 0x2b0000
	s_addc_u32 s59, s77, 0
	s_mov_b32 m0, s85
	s_nop 0
	global_load_lds_dwordx4 v1, s[58:59]
	s_nop 0
	s_mov_b32 m0, s86
	s_nop 0
	global_load_lds_dwordx4 v141, s[58:59]
	s_waitcnt vmcnt(8)
	s_waitcnt lgkmcnt(0)
	s_barrier
	s_setprio 1
	s_waitcnt lgkmcnt(7)
	v_mfma_f32_16x16x32_bf16 v[126:129], v[248:251], v[180:183], v[126:129]
	v_mfma_f32_16x16x32_bf16 v[126:129], v[152:155], v[184:187], v[126:129]
	v_mfma_f32_16x16x32_bf16 v[122:125], v[160:163], v[184:187], v[122:125]
	v_mfma_f32_16x16x32_bf16 v[122:125], v[156:159], v[180:183], v[122:125]
	v_mfma_f32_16x16x32_bf16 v[118:121], v[164:167], v[180:183], v[118:121]
	v_mfma_f32_16x16x32_bf16 v[118:121], v[168:171], v[184:187], v[118:121]
	v_mfma_f32_16x16x32_bf16 v[114:117], v[176:179], v[184:187], v[114:117]
	v_mfma_f32_16x16x32_bf16 v[114:117], v[172:175], v[180:183], v[114:117]
	v_mfma_f32_16x16x32_bf16 v[98:101], v[172:175], v[188:191], v[98:101]
	v_mfma_f32_16x16x32_bf16 v[98:101], v[176:179], v[192:195], v[98:101]
	v_mfma_f32_16x16x32_bf16 v[102:105], v[168:171], v[192:195], v[102:105]
	v_mfma_f32_16x16x32_bf16 v[102:105], v[164:167], v[188:191], v[102:105]
	v_mfma_f32_16x16x32_bf16 v[106:109], v[156:159], v[188:191], v[106:109]
	v_mfma_f32_16x16x32_bf16 v[106:109], v[160:163], v[192:195], v[106:109]
	v_mfma_f32_16x16x32_bf16 v[110:113], v[152:155], v[192:195], v[110:113]
	v_mfma_f32_16x16x32_bf16 v[110:113], v[248:251], v[188:191], v[110:113]
	v_mfma_f32_16x16x32_bf16 v[94:97], v[248:251], v[196:199], v[94:97]
	v_mfma_f32_16x16x32_bf16 v[94:97], v[152:155], v[200:203], v[94:97]
	v_mfma_f32_16x16x32_bf16 v[90:93], v[160:163], v[200:203], v[90:93]
	v_mfma_f32_16x16x32_bf16 v[90:93], v[156:159], v[196:199], v[90:93]
	v_mfma_f32_16x16x32_bf16 v[86:89], v[164:167], v[196:199], v[86:89]
	v_mfma_f32_16x16x32_bf16 v[86:89], v[168:171], v[200:203], v[86:89]
	v_mfma_f32_16x16x32_bf16 v[82:85], v[176:179], v[200:203], v[82:85]
	v_mfma_f32_16x16x32_bf16 v[82:85], v[172:175], v[196:199], v[82:85]
	v_mfma_f32_16x16x32_bf16 v[66:69], v[172:175], v[204:207], v[66:69]
	v_mfma_f32_16x16x32_bf16 v[66:69], v[176:179], v[208:211], v[66:69]
	v_mfma_f32_16x16x32_bf16 v[70:73], v[168:171], v[208:211], v[70:73]
	v_mfma_f32_16x16x32_bf16 v[70:73], v[164:167], v[204:207], v[70:73]
	v_mfma_f32_16x16x32_bf16 v[74:77], v[156:159], v[204:207], v[74:77]
	v_mfma_f32_16x16x32_bf16 v[74:77], v[160:163], v[208:211], v[74:77]
	v_mfma_f32_16x16x32_bf16 v[78:81], v[152:155], v[208:211], v[78:81]
	s_setprio 2
	s_barrier
	v_mfma_f32_16x16x32_bf16 v[78:81], v[248:251], v[204:207], v[78:81]
	s_setprio 0
	ds_read_b128 v[180:183], v147 offset:49152
	ds_read_b128 v[184:187], v147 offset:50176
	ds_read_b128 v[188:191], v147 offset:51200
	ds_read_b128 v[192:195], v147 offset:52224
	ds_read_b128 v[196:199], v147 offset:53248
	ds_read_b128 v[200:203], v147 offset:54272
	ds_read_b128 v[252:255], v147 offset:55296
	ds_read_b128 v[208:211], v147 offset:56320
	s_add_u32 s58, s66, 0x80
	s_addc_u32 s59, s67, 0
	s_mov_b32 m0, s88
	s_nop 0
	global_load_lds_dwordx4 v140, s[58:59]
	s_nop 0
	s_mov_b32 m0, s89
	s_nop 0
	global_load_lds_dwordx4 v142, s[58:59]
	s_add_u32 s58, s66, 0x2b0080
	s_addc_u32 s59, s67, 0
	s_mov_b32 m0, s92
	s_nop 0
	global_load_lds_dwordx4 v140, s[58:59]
	s_nop 0
	s_mov_b32 m0, s93
	s_nop 0
	global_load_lds_dwordx4 v142, s[58:59]
	s_nop 0
	s_mov_b32 m0, s90
	s_nop 0
	global_load_lds_dwordx4 v1, s[62:63]
	s_nop 0
	s_mov_b32 m0, s91
	s_nop 0
	global_load_lds_dwordx4 v141, s[62:63]
	s_waitcnt vmcnt(8)
	s_waitcnt lgkmcnt(0)
	s_barrier
	s_setprio 1
	s_waitcnt lgkmcnt(7)
	v_mfma_f32_16x16x32_bf16 v[62:65], v[248:251], v[180:183], v[62:65]
	v_mfma_f32_16x16x32_bf16 v[62:65], v[152:155], v[184:187], v[62:65]
	v_mfma_f32_16x16x32_bf16 v[58:61], v[160:163], v[184:187], v[58:61]
	v_mfma_f32_16x16x32_bf16 v[58:61], v[156:159], v[180:183], v[58:61]
	v_mfma_f32_16x16x32_bf16 v[54:57], v[164:167], v[180:183], v[54:57]
	v_mfma_f32_16x16x32_bf16 v[54:57], v[168:171], v[184:187], v[54:57]
	v_mfma_f32_16x16x32_bf16 v[50:53], v[176:179], v[184:187], v[50:53]
	v_mfma_f32_16x16x32_bf16 v[50:53], v[172:175], v[180:183], v[50:53]
	v_mfma_f32_16x16x32_bf16 v[34:37], v[172:175], v[188:191], v[34:37]
	v_mfma_f32_16x16x32_bf16 v[34:37], v[176:179], v[192:195], v[34:37]
	v_mfma_f32_16x16x32_bf16 v[38:41], v[168:171], v[192:195], v[38:41]
	v_mfma_f32_16x16x32_bf16 v[38:41], v[164:167], v[188:191], v[38:41]
	v_mfma_f32_16x16x32_bf16 v[42:45], v[156:159], v[188:191], v[42:45]
	v_mfma_f32_16x16x32_bf16 v[42:45], v[160:163], v[192:195], v[42:45]
	v_mfma_f32_16x16x32_bf16 v[46:49], v[152:155], v[192:195], v[46:49]
	v_mfma_f32_16x16x32_bf16 v[46:49], v[248:251], v[188:191], v[46:49]
	v_mfma_f32_16x16x32_bf16 v[30:33], v[248:251], v[196:199], v[30:33]
	v_mfma_f32_16x16x32_bf16 v[30:33], v[152:155], v[200:203], v[30:33]
	v_mfma_f32_16x16x32_bf16 v[26:29], v[160:163], v[200:203], v[26:29]
	v_mfma_f32_16x16x32_bf16 v[26:29], v[156:159], v[196:199], v[26:29]
	v_mfma_f32_16x16x32_bf16 v[22:25], v[164:167], v[196:199], v[22:25]
	v_mfma_f32_16x16x32_bf16 v[22:25], v[168:171], v[200:203], v[22:25]
	v_mfma_f32_16x16x32_bf16 v[18:21], v[176:179], v[200:203], v[18:21]
	v_mfma_f32_16x16x32_bf16 v[18:21], v[172:175], v[196:199], v[18:21]
	v_mfma_f32_16x16x32_bf16 v[2:5], v[172:175], v[252:255], v[2:5]
	v_mfma_f32_16x16x32_bf16 v[2:5], v[176:179], v[208:211], v[2:5]
	v_mfma_f32_16x16x32_bf16 v[6:9], v[168:171], v[208:211], v[6:9]
	v_mfma_f32_16x16x32_bf16 v[6:9], v[164:167], v[252:255], v[6:9]
	v_mfma_f32_16x16x32_bf16 v[10:13], v[156:159], v[252:255], v[10:13]
	v_mfma_f32_16x16x32_bf16 v[10:13], v[160:163], v[208:211], v[10:13]
	v_mfma_f32_16x16x32_bf16 v[14:17], v[152:155], v[208:211], v[14:17]
	s_setprio 2
	s_barrier
	v_mfma_f32_16x16x32_bf16 v[14:17], v[248:251], v[252:255], v[14:17]
	s_setprio 0
	s_add_i32 s57, s57, 2
	s_add_u32 s53, s53, 0x100
	s_addc_u32 s54, s54, 0
	s_add_u32 s55, s55, 0x100
	s_addc_u32 s56, s56, 0
	s_add_u32 s50, s50, 0x100
	s_addc_u32 s51, s51, 0
	s_cmpk_gt_u32 s57, 0xa9
	s_cbranch_scc0 .LBB0_234
	s_and_b64 vcc, exec, s[16:17]
	s_cbranch_vccz .LBB0_237
	s_barrier

; #define PG8_STAGE(bufoff, gbase, voff) do { _Pragma("unroll") for (int _i = 0; _i < 2; ++_i) \
;         asm volatile("s_mov_b32 m0, %2\n\ts_nop 0\n\tglobal_load_lds_dwordx4 %0, %1" :: "v"((voff)[_i]), "s"((const char*)(gbase)), "s"(ldsbase + (unsigned)(bufoff) + ldsw + (unsigned)_i * 8192u) : "memory", "m0"); } while (0)
; #define PG8_LDA(dst, b, h) do { _Pragma("unroll") for (int m = 0; m < 4; ++m) _Pragma("unroll") for (int k = 0; k < 2; ++k) dst[m][k] = *(const PG8_LAS bf16x8*)(lds + PG8_SA(b, h) + aoff + m * 2048 + k * 1024); } while (0)
; #define PG8_LDB(dst, b, h) do { _Pragma("unroll") for (int n = 0; n < 2; ++n) _Pragma("unroll") for (int k = 0; k < 2; ++k) dst[n][k] = *(const PG8_LAS bf16x8*)(lds + PG8_SB(b, h) + boff + n * 2048 + k * 1024); } while (0)
; #define PG8_MMA(ai, bj, At, Bt) do { __builtin_amdgcn_s_setprio(1); _Pragma("unroll") for (int m = 0; m < 4; ++m) _Pragma("unroll") for (int n = 0; n < 2; ++n) _Pragma("unroll") for (int k = 0; k < 2; ++k) \
;         acc[ai][bj][m][n] = __builtin_amdgcn_mfma_f32_16x16x32_bf16(Bt[n][k], At[m][k], acc[ai][bj][m][n], 0, 0, 0); __builtin_amdgcn_s_setprio(0); } while (0)
; template <class Epi, class Sched, bool ALIGN_EPI = false, bool SP2 = false>
; __device__ __forceinline__ void gemm_phase(PG8_LAS unsigned char* lds, const Gemm g, const Sched& S, const Epi& E) {
;     ...
;             PG8_LDB(B0, 0, 0); PG8_LDB(B1, 0, 1); PG8_SCHED; PG8_LDA(At, 0, 0); PG8_STAGE(PG8_SA(1, 1), a1 + hstep, voffA);
;             PG8_WAIT_V(8); PG8_WAIT_L(0); PG8_BAR; PG8_MMA(0, 0, At, B0); PG8_MMA(0, 1, At, B1); PG8_BAR; PG8_SCHED;
;             PG8_LDA(At, 0, 1); PG8_STAGE(PG8_SB(0, 0), b2, voffB); PG8_STAGE(PG8_SB(0, 1), b2 + hstep, voffB); PG8_STAGE(PG8_SA(0, 0), a2, voffA);
;             PG8_WAIT_V(8); PG8_WAIT_L(0); PG8_BAR; PG8_MMA(1, 0, At, B0); PG8_MMA(1, 1, At, B1); PG8_BAR; PG8_SCHED;
;             PG8_LDB(B0, 1, 0); PG8_LDB(B1, 1, 1); PG8_SCHED; PG8_LDA(At, 1, 0); PG8_STAGE(PG8_SA(0, 1), a2 + hstep, voffA);
;             PG8_WAIT_V(8); PG8_WAIT_L(0); PG8_BAR; PG8_MMA(0, 0, At, B0); PG8_MMA(0, 1, At, B1); PG8_BAR; PG8_SCHED;
;             PG8_LDA(At, 1, 1); PG8_STAGE(PG8_SB(1, 0), b3, voffB); PG8_STAGE(PG8_SB(1, 1), b3 + hstep, voffB); PG8_STAGE(PG8_SA(1, 0), a3, voffA);
;             PG8_WAIT_V(8); PG8_WAIT_L(0); PG8_BAR; PG8_MMA(1, 0, At, B0); PG8_MMA(1, 1, At, B1); PG8_BAR; PG8_SCHED;
.LBB0_620:
	v_add_u32_e32 v3, 0x10000, v199
	ds_read_b128 v[134:137], v3
	ds_read_b128 v[138:141], v3 offset:1024
	ds_read_b128 v[142:145], v3 offset:2048
	ds_read_b128 v[146:149], v3 offset:3072
	v_add_u32_e32 v3, 0x14000, v199
	s_add_u32 s44, s42, 0x100
	ds_read_b128 v[158:161], v3
	ds_read_b128 v[162:165], v3 offset:1024
	ds_read_b128 v[166:169], v3 offset:2048
	ds_read_b128 v[170:173], v3 offset:3072
	s_addc_u32 s45, s43, 0
	s_cmp_eq_u32 s92, 60
	s_cselect_b32 s56, s88, s44
	s_cselect_b32 s57, s23, s45
	s_cselect_b32 s47, s19, s91
	s_cselect_b32 s46, s89, s90
	s_add_u32 s50, s56, 0x80
	s_addc_u32 s51, s57, 0
	s_add_u32 s54, s46, 0x80
	s_addc_u32 s55, s47, 0
	ds_read_b128 v[174:177], v200
	ds_read_b128 v[178:181], v200 offset:1024
	ds_read_b128 v[182:185], v200 offset:2048
	ds_read_b128 v[186:189], v200 offset:3072
	ds_read_b128 v[190:193], v200 offset:4096
	ds_read_b128 v[202:205], v200 offset:5120
	ds_read_b128 v[206:209], v200 offset:6144
	ds_read_b128 v[210:213], v200 offset:7168
	s_add_u32 s42, s42, 0x100080
	s_addc_u32 s43, s43, 0
	s_mov_b32 m0, s85
	s_nop 0
	global_load_lds_dwordx4 v1, s[42:43]
	s_nop 0
	s_mov_b32 m0, s86
	s_nop 0
	global_load_lds_dwordx4 v195, s[42:43]
	s_waitcnt vmcnt(8)
	s_waitcnt lgkmcnt(0)
	s_barrier
	s_setprio 1
	s_waitcnt lgkmcnt(7)
	v_mfma_f32_16x16x32_bf16 v[130:133], v[134:137], v[174:177], v[130:133]
	v_mfma_f32_16x16x32_bf16 v[126:129], v[142:145], v[174:177], v[126:129]
	v_mfma_f32_16x16x32_bf16 v[122:125], v[134:137], v[182:185], v[122:125]
	v_mfma_f32_16x16x32_bf16 v[118:121], v[142:145], v[182:185], v[118:121]
	v_mfma_f32_16x16x32_bf16 v[114:117], v[134:137], v[190:193], v[114:117]
	v_mfma_f32_16x16x32_bf16 v[110:113], v[142:145], v[190:193], v[110:113]
	v_mfma_f32_16x16x32_bf16 v[106:109], v[134:137], v[206:209], v[106:109]
	v_mfma_f32_16x16x32_bf16 v[102:105], v[142:145], v[206:209], v[102:105]
	v_mfma_f32_16x16x32_bf16 v[130:133], v[138:141], v[178:181], v[130:133]
	v_mfma_f32_16x16x32_bf16 v[126:129], v[146:149], v[178:181], v[126:129]
	v_mfma_f32_16x16x32_bf16 v[122:125], v[138:141], v[186:189], v[122:125]
	v_mfma_f32_16x16x32_bf16 v[118:121], v[146:149], v[186:189], v[118:121]
	v_mfma_f32_16x16x32_bf16 v[114:117], v[138:141], v[202:205], v[114:117]
	v_mfma_f32_16x16x32_bf16 v[110:113], v[146:149], v[202:205], v[110:113]
	v_mfma_f32_16x16x32_bf16 v[106:109], v[138:141], v[210:213], v[106:109]
	v_mfma_f32_16x16x32_bf16 v[102:105], v[146:149], v[210:213], v[102:105]
	v_mfma_f32_16x16x32_bf16 v[66:69], v[158:161], v[174:177], v[66:69]
	v_mfma_f32_16x16x32_bf16 v[62:65], v[166:169], v[174:177], v[62:65]
	v_mfma_f32_16x16x32_bf16 v[58:61], v[158:161], v[182:185], v[58:61]
	v_mfma_f32_16x16x32_bf16 v[54:57], v[166:169], v[182:185], v[54:57]
	v_mfma_f32_16x16x32_bf16 v[50:53], v[158:161], v[190:193], v[50:53]
	v_mfma_f32_16x16x32_bf16 v[46:49], v[166:169], v[190:193], v[46:49]
	v_mfma_f32_16x16x32_bf16 v[42:45], v[158:161], v[206:209], v[42:45]
	v_mfma_f32_16x16x32_bf16 v[38:41], v[166:169], v[206:209], v[38:41]
	v_mfma_f32_16x16x32_bf16 v[66:69], v[162:165], v[178:181], v[66:69]
	v_mfma_f32_16x16x32_bf16 v[62:65], v[170:173], v[178:181], v[62:65]
	v_mfma_f32_16x16x32_bf16 v[58:61], v[162:165], v[186:189], v[58:61]
	v_mfma_f32_16x16x32_bf16 v[54:57], v[170:173], v[186:189], v[54:57]
	v_mfma_f32_16x16x32_bf16 v[50:53], v[162:165], v[202:205], v[50:53]
	v_mfma_f32_16x16x32_bf16 v[46:49], v[170:173], v[202:205], v[46:49]
	v_mfma_f32_16x16x32_bf16 v[42:45], v[162:165], v[210:213], v[42:45]
	s_setprio 2
	s_barrier
	v_mfma_f32_16x16x32_bf16 v[38:41], v[170:173], v[210:213], v[38:41]
	s_setprio 0
	ds_read_b128 v[174:177], v200 offset:16384
	ds_read_b128 v[178:181], v200 offset:17408
	ds_read_b128 v[182:185], v200 offset:18432
	ds_read_b128 v[186:189], v200 offset:19456
	ds_read_b128 v[190:193], v200 offset:20480
	ds_read_b128 v[202:205], v200 offset:21504
	ds_read_b128 v[206:209], v200 offset:22528
	ds_read_b128 v[252:255], v200 offset:23552
	s_mov_b32 m0, s63
	s_nop 0
	global_load_lds_dwordx4 v194, s[46:47]
	s_add_u32 s42, s46, 0x100000
	s_mov_b32 m0, s64
	s_nop 0
	global_load_lds_dwordx4 v196, s[46:47]
	s_addc_u32 s43, s47, 0
	s_mov_b32 m0, s65
	s_nop 0
	global_load_lds_dwordx4 v194, s[42:43]
	s_nop 0
	s_mov_b32 m0, s66
	s_nop 0
	global_load_lds_dwordx4 v196, s[42:43]
	s_nop 0
	s_mov_b32 m0, s62
	s_nop 0
	global_load_lds_dwordx4 v1, s[56:57]
	s_nop 0
	s_mov_b32 m0, s67
	s_nop 0
	global_load_lds_dwordx4 v195, s[56:57]
	s_waitcnt vmcnt(8)
	s_waitcnt lgkmcnt(0)
	s_barrier
	s_setprio 1
	s_waitcnt lgkmcnt(7)
	v_mfma_f32_16x16x32_bf16 v[98:101], v[134:137], v[174:177], v[98:101]
	v_mfma_f32_16x16x32_bf16 v[94:97], v[142:145], v[174:177], v[94:97]
	v_mfma_f32_16x16x32_bf16 v[90:93], v[134:137], v[182:185], v[90:93]
	v_mfma_f32_16x16x32_bf16 v[86:89], v[142:145], v[182:185], v[86:89]
	v_mfma_f32_16x16x32_bf16 v[82:85], v[134:137], v[190:193], v[82:85]
	v_mfma_f32_16x16x32_bf16 v[78:81], v[142:145], v[190:193], v[78:81]
	v_mfma_f32_16x16x32_bf16 v[74:77], v[134:137], v[206:209], v[74:77]
	v_mfma_f32_16x16x32_bf16 v[70:73], v[142:145], v[206:209], v[70:73]
	v_mfma_f32_16x16x32_bf16 v[98:101], v[138:141], v[178:181], v[98:101]
	v_mfma_f32_16x16x32_bf16 v[94:97], v[146:149], v[178:181], v[94:97]
	v_mfma_f32_16x16x32_bf16 v[90:93], v[138:141], v[186:189], v[90:93]
	v_mfma_f32_16x16x32_bf16 v[86:89], v[146:149], v[186:189], v[86:89]
	v_mfma_f32_16x16x32_bf16 v[82:85], v[138:141], v[202:205], v[82:85]
	v_mfma_f32_16x16x32_bf16 v[78:81], v[146:149], v[202:205], v[78:81]
	v_mfma_f32_16x16x32_bf16 v[74:77], v[138:141], v[252:255], v[74:77]
	v_mfma_f32_16x16x32_bf16 v[70:73], v[146:149], v[252:255], v[70:73]
	v_mfma_f32_16x16x32_bf16 v[34:37], v[158:161], v[174:177], v[34:37]
	v_mfma_f32_16x16x32_bf16 v[30:33], v[166:169], v[174:177], v[30:33]
	v_mfma_f32_16x16x32_bf16 v[26:29], v[158:161], v[182:185], v[26:29]
	v_mfma_f32_16x16x32_bf16 v[22:25], v[166:169], v[182:185], v[22:25]
	v_mfma_f32_16x16x32_bf16 v[18:21], v[158:161], v[190:193], v[18:21]
	v_mfma_f32_16x16x32_bf16 v[14:17], v[166:169], v[190:193], v[14:17]
	v_mfma_f32_16x16x32_bf16 v[10:13], v[158:161], v[206:209], v[10:13]
	v_mfma_f32_16x16x32_bf16 v[4:7], v[166:169], v[206:209], v[6:9]
	v_mfma_f32_16x16x32_bf16 v[34:37], v[162:165], v[178:181], v[34:37]
	v_mfma_f32_16x16x32_bf16 v[30:33], v[170:173], v[178:181], v[30:33]
	v_mfma_f32_16x16x32_bf16 v[26:29], v[162:165], v[186:189], v[26:29]
	v_mfma_f32_16x16x32_bf16 v[22:25], v[170:173], v[186:189], v[22:25]
	v_mfma_f32_16x16x32_bf16 v[18:21], v[162:165], v[202:205], v[18:21]
	v_mfma_f32_16x16x32_bf16 v[14:17], v[170:173], v[202:205], v[14:17]
	v_mfma_f32_16x16x32_bf16 v[10:13], v[162:165], v[252:255], v[10:13]
	s_setprio 2
	s_barrier
; #define PG8_STAGE(bufoff, gbase, voff) do { _Pragma("unroll") for (int _i = 0; _i < 2; ++_i) \
;         asm volatile("s_mov_b32 m0, %2\n\ts_nop 0\n\tglobal_load_lds_dwordx4 %0, %1" :: "v"((voff)[_i]), "s"((const char*)(gbase)), "s"(ldsbase + (unsigned)(bufoff) + ldsw + (unsigned)_i * 8192u) : "memory", "m0"); } while (0)
; #define PG8_LDA(dst, b, h) do { _Pragma("unroll") for (int m = 0; m < 4; ++m) _Pragma("unroll") for (int k = 0; k < 2; ++k) dst[m][k] = *(const PG8_LAS bf16x8*)(lds + PG8_SA(b, h) + aoff + m * 2048 + k * 1024); } while (0)
; #define PG8_LDB(dst, b, h) do { _Pragma("unroll") for (int n = 0; n < 2; ++n) _Pragma("unroll") for (int k = 0; k < 2; ++k) dst[n][k] = *(const PG8_LAS bf16x8*)(lds + PG8_SB(b, h) + boff + n * 2048 + k * 1024); } while (0)
; #define PG8_MMA(ai, bj, At, Bt) do { __builtin_amdgcn_s_setprio(1); _Pragma("unroll") for (int m = 0; m < 4; ++m) _Pragma("unroll") for (int n = 0; n < 2; ++n) _Pragma("unroll") for (int k = 0; k < 2; ++k) \
;         acc[ai][bj][m][n] = __builtin_amdgcn_mfma_f32_16x16x32_bf16(Bt[n][k], At[m][k], acc[ai][bj][m][n], 0, 0, 0); __builtin_amdgcn_s_setprio(0); } while (0)
; #define PG8_WAIT_V(n) asm volatile("s_waitcnt vmcnt(" #n ")" ::: "memory")
; #define PG8_WAIT_L(n) asm volatile("s_waitcnt lgkmcnt(" #n ")" ::: "memory")
; #define PG8_BAR __builtin_amdgcn_s_barrier()
; #define PG8_SCHED __builtin_amdgcn_sched_barrier(0)
; template <class Epi, class Sched, bool ALIGN_EPI = false, bool SP2 = false>
; __device__ __forceinline__ void gemm_phase(PG8_LAS unsigned char* lds, const Gemm g, const Sched& S, const Epi& E) {
;     ...
;             if constexpr (epi_has_mid<Epi>::value) { if (t == Epi::MID_T) E.mid(acc, cur, wr, wc, fr, fq); }
;     ...
;             PG8_WAIT_V(8); PG8_WAIT_L(0); PG8_BAR; PG8_MMA(1, 0, At, B0); PG8_MMA(1, 1, At, B1); PG8_BAR; PG8_SCHED;
;             PG8_LDB(B0, 1, 0); PG8_LDB(B1, 1, 1); PG8_SCHED; PG8_LDA(At, 1, 0); PG8_STAGE(PG8_SA(0, 1), a2 + hstep, voffA);
;             PG8_WAIT_V(8); PG8_WAIT_L(0); PG8_BAR; PG8_MMA(0, 0, At, B0); PG8_MMA(0, 1, At, B1); PG8_BAR; PG8_SCHED;
;             PG8_LDA(At, 1, 1); PG8_STAGE(PG8_SB(1, 0), b3, voffB); PG8_STAGE(PG8_SB(1, 1), b3 + hstep, voffB); PG8_STAGE(PG8_SA(1, 0), a3, voffA);
;             PG8_WAIT_V(8); PG8_WAIT_L(0); PG8_BAR; PG8_MMA(1, 0, At, B0); PG8_MMA(1, 1, At, B1); PG8_BAR; PG8_SCHED;
	v_mfma_f32_16x16x32_bf16 v[4:7], v[170:173], v[252:255], v[4:7]
	s_setprio 0
	v_add_u32_e32 v3, 0x18000, v199
	ds_read_b128 v[134:137], v3
	ds_read_b128 v[138:141], v3 offset:1024
	ds_read_b128 v[142:145], v3 offset:2048
	ds_read_b128 v[146:149], v3 offset:3072
	v_add_u32_e32 v3, 0x1c000, v199
	ds_read_b128 v[158:161], v3
	ds_read_b128 v[162:165], v3 offset:1024
	ds_read_b128 v[166:169], v3 offset:2048
	ds_read_b128 v[248:251], v3 offset:3072
	ds_read_b128 v[174:177], v200 offset:32768
	ds_read_b128 v[178:181], v200 offset:33792
	ds_read_b128 v[182:185], v200 offset:34816
	ds_read_b128 v[186:189], v200 offset:35840
	ds_read_b128 v[190:193], v200 offset:36864
	ds_read_b128 v[202:205], v200 offset:37888
	ds_read_b128 v[206:209], v200 offset:38912
	ds_read_b128 v[210:213], v200 offset:39936
	s_add_u32 s42, s56, 0x100000
	s_addc_u32 s43, s57, 0
	s_mov_b32 m0, s76
	s_nop 0
	global_load_lds_dwordx4 v1, s[42:43]
	s_nop 0
	s_mov_b32 m0, s77
	s_nop 0
	global_load_lds_dwordx4 v195, s[42:43]
	s_waitcnt vmcnt(8)
	s_waitcnt lgkmcnt(0)
	s_barrier
	s_setprio 1
	s_waitcnt lgkmcnt(7)
	v_mfma_f32_16x16x32_bf16 v[130:133], v[134:137], v[174:177], v[130:133]
	v_mfma_f32_16x16x32_bf16 v[126:129], v[142:145], v[174:177], v[126:129]
	v_mfma_f32_16x16x32_bf16 v[122:125], v[134:137], v[182:185], v[122:125]
	v_mfma_f32_16x16x32_bf16 v[118:121], v[142:145], v[182:185], v[118:121]
	v_mfma_f32_16x16x32_bf16 v[114:117], v[134:137], v[190:193], v[114:117]
	v_mfma_f32_16x16x32_bf16 v[110:113], v[142:145], v[190:193], v[110:113]
	v_mfma_f32_16x16x32_bf16 v[106:109], v[134:137], v[206:209], v[106:109]
	v_mfma_f32_16x16x32_bf16 v[102:105], v[142:145], v[206:209], v[102:105]
	v_mfma_f32_16x16x32_bf16 v[130:133], v[138:141], v[178:181], v[130:133]
	v_mfma_f32_16x16x32_bf16 v[126:129], v[146:149], v[178:181], v[126:129]
	v_mfma_f32_16x16x32_bf16 v[122:125], v[138:141], v[186:189], v[122:125]
	v_mfma_f32_16x16x32_bf16 v[118:121], v[146:149], v[186:189], v[118:121]
	v_mfma_f32_16x16x32_bf16 v[114:117], v[138:141], v[202:205], v[114:117]
	v_mfma_f32_16x16x32_bf16 v[110:113], v[146:149], v[202:205], v[110:113]
	v_mfma_f32_16x16x32_bf16 v[106:109], v[138:141], v[210:213], v[106:109]
	v_mfma_f32_16x16x32_bf16 v[102:105], v[146:149], v[210:213], v[102:105]
	v_mfma_f32_16x16x32_bf16 v[66:69], v[158:161], v[174:177], v[66:69]
	v_mfma_f32_16x16x32_bf16 v[62:65], v[166:169], v[174:177], v[62:65]
	v_mfma_f32_16x16x32_bf16 v[58:61], v[158:161], v[182:185], v[58:61]
	v_mfma_f32_16x16x32_bf16 v[54:57], v[166:169], v[182:185], v[54:57]
	v_mfma_f32_16x16x32_bf16 v[50:53], v[158:161], v[190:193], v[50:53]
	v_mfma_f32_16x16x32_bf16 v[46:49], v[166:169], v[190:193], v[46:49]
	v_mfma_f32_16x16x32_bf16 v[42:45], v[158:161], v[206:209], v[42:45]
	v_mfma_f32_16x16x32_bf16 v[38:41], v[166:169], v[206:209], v[38:41]
	v_mfma_f32_16x16x32_bf16 v[66:69], v[162:165], v[178:181], v[66:69]
	v_mfma_f32_16x16x32_bf16 v[62:65], v[248:251], v[178:181], v[62:65]
	v_mfma_f32_16x16x32_bf16 v[58:61], v[162:165], v[186:189], v[58:61]
	v_mfma_f32_16x16x32_bf16 v[54:57], v[248:251], v[186:189], v[54:57]
	v_mfma_f32_16x16x32_bf16 v[50:53], v[162:165], v[202:205], v[50:53]
	v_mfma_f32_16x16x32_bf16 v[46:49], v[248:251], v[202:205], v[46:49]
	v_mfma_f32_16x16x32_bf16 v[42:45], v[162:165], v[210:213], v[42:45]
	s_setprio 2
	s_barrier
	v_mfma_f32_16x16x32_bf16 v[38:41], v[248:251], v[210:213], v[38:41]
	s_setprio 0
	ds_read_b128 v[174:177], v200 offset:49152
	ds_read_b128 v[178:181], v200 offset:50176
	ds_read_b128 v[182:185], v200 offset:51200
	ds_read_b128 v[186:189], v200 offset:52224
	ds_read_b128 v[190:193], v200 offset:53248
	ds_read_b128 v[202:205], v200 offset:54272
	ds_read_b128 v[206:209], v200 offset:55296
	ds_read_b128 v[252:255], v200 offset:56320
	s_mov_b32 m0, s78
	s_nop 0
	global_load_lds_dwordx4 v194, s[54:55]
	s_add_u32 s42, s46, 0x100080
	s_mov_b32 m0, s79
	s_nop 0
	global_load_lds_dwordx4 v196, s[54:55]
	s_addc_u32 s43, s47, 0
	s_mov_b32 m0, s83
	s_nop 0
	global_load_lds_dwordx4 v194, s[42:43]
	s_nop 0
	s_mov_b32 m0, s84
	s_nop 0
	global_load_lds_dwordx4 v196, s[42:43]
	s_nop 0
	s_mov_b32 m0, s80
	s_nop 0
	global_load_lds_dwordx4 v1, s[50:51]
	s_nop 0
	s_mov_b32 m0, s82
	s_nop 0
	global_load_lds_dwordx4 v195, s[50:51]
	s_waitcnt vmcnt(8)
	s_waitcnt lgkmcnt(0)
	s_barrier
	s_setprio 1
	s_waitcnt lgkmcnt(7)
	v_mfma_f32_16x16x32_bf16 v[98:101], v[134:137], v[174:177], v[98:101]
	v_mfma_f32_16x16x32_bf16 v[94:97], v[142:145], v[174:177], v[94:97]
	v_mfma_f32_16x16x32_bf16 v[90:93], v[134:137], v[182:185], v[90:93]
	v_mfma_f32_16x16x32_bf16 v[86:89], v[142:145], v[182:185], v[86:89]
	v_mfma_f32_16x16x32_bf16 v[82:85], v[134:137], v[190:193], v[82:85]
	v_mfma_f32_16x16x32_bf16 v[78:81], v[142:145], v[190:193], v[78:81]
	v_mfma_f32_16x16x32_bf16 v[74:77], v[134:137], v[206:209], v[74:77]
	v_mfma_f32_16x16x32_bf16 v[70:73], v[142:145], v[206:209], v[70:73]
	v_mfma_f32_16x16x32_bf16 v[98:101], v[138:141], v[178:181], v[98:101]
	v_mfma_f32_16x16x32_bf16 v[94:97], v[146:149], v[178:181], v[94:97]
	v_mfma_f32_16x16x32_bf16 v[90:93], v[138:141], v[186:189], v[90:93]
	v_mfma_f32_16x16x32_bf16 v[86:89], v[146:149], v[186:189], v[86:89]
	v_mfma_f32_16x16x32_bf16 v[82:85], v[138:141], v[202:205], v[82:85]
	v_mfma_f32_16x16x32_bf16 v[78:81], v[146:149], v[202:205], v[78:81]
	v_mfma_f32_16x16x32_bf16 v[74:77], v[138:141], v[252:255], v[74:77]
	v_mfma_f32_16x16x32_bf16 v[70:73], v[146:149], v[252:255], v[70:73]
	v_mfma_f32_16x16x32_bf16 v[34:37], v[158:161], v[174:177], v[34:37]
	v_mfma_f32_16x16x32_bf16 v[30:33], v[166:169], v[174:177], v[30:33]
	v_mfma_f32_16x16x32_bf16 v[26:29], v[158:161], v[182:185], v[26:29]
	v_mfma_f32_16x16x32_bf16 v[22:25], v[166:169], v[182:185], v[22:25]
	v_mfma_f32_16x16x32_bf16 v[18:21], v[158:161], v[190:193], v[18:21]
	v_mfma_f32_16x16x32_bf16 v[14:17], v[166:169], v[190:193], v[14:17]
	v_mfma_f32_16x16x32_bf16 v[8:11], v[158:161], v[206:209], v[10:13]
	v_mfma_f32_16x16x32_bf16 v[4:7], v[166:169], v[206:209], v[4:7]
	v_mfma_f32_16x16x32_bf16 v[34:37], v[162:165], v[178:181], v[34:37]
	v_mfma_f32_16x16x32_bf16 v[30:33], v[248:251], v[178:181], v[30:33]
	v_mfma_f32_16x16x32_bf16 v[26:29], v[162:165], v[186:189], v[26:29]
	v_mfma_f32_16x16x32_bf16 v[22:25], v[248:251], v[186:189], v[22:25]
	v_mfma_f32_16x16x32_bf16 v[18:21], v[162:165], v[202:205], v[18:21]
	v_mfma_f32_16x16x32_bf16 v[14:17], v[248:251], v[202:205], v[14:17]
	v_mfma_f32_16x16x32_bf16 v[10:13], v[162:165], v[252:255], v[8:11]
	v_mfma_f32_16x16x32_bf16 v[6:9], v[248:251], v[252:255], v[4:7]
	s_setprio 0
	s_barrier
	s_add_i32 s92, s92, 2
	s_add_u32 s90, s90, 0x100
	s_addc_u32 s91, s91, 0
	s_cmp_gt_u32 s92, 61
	s_cbranch_scc1 .LBB0_622
	s_mov_b64 s[42:43], s[44:45]
	s_cmp_lg_u32 s92, 30
	s_cbranch_scc0 .LBB0_619
	s_branch .LBB0_620

; #define PG8_STAGE(bufoff, gbase, voff) do { _Pragma("unroll") for (int _i = 0; _i < 2; ++_i) \
;         asm volatile("s_mov_b32 m0, %2\n\ts_nop 0\n\tglobal_load_lds_dwordx4 %0, %1" :: "v"((voff)[_i]), "s"((const char*)(gbase)), "s"(ldsbase + (unsigned)(bufoff) + ldsw + (unsigned)_i * 8192u) : "memory", "m0"); } while (0)
; #define PG8_LDA(dst, b, h) do { _Pragma("unroll") for (int m = 0; m < 4; ++m) _Pragma("unroll") for (int k = 0; k < 2; ++k) dst[m][k] = *(const PG8_LAS bf16x8*)(lds + PG8_SA(b, h) + aoff + m * 2048 + k * 1024); } while (0)
; #define PG8_LDB(dst, b, h) do { _Pragma("unroll") for (int n = 0; n < 2; ++n) _Pragma("unroll") for (int k = 0; k < 2; ++k) dst[n][k] = *(const PG8_LAS bf16x8*)(lds + PG8_SB(b, h) + boff + n * 2048 + k * 1024); } while (0)
; #define PG8_MMA(ai, bj, At, Bt) do { __builtin_amdgcn_s_setprio(1); _Pragma("unroll") for (int m = 0; m < 4; ++m) _Pragma("unroll") for (int n = 0; n < 2; ++n) _Pragma("unroll") for (int k = 0; k < 2; ++k) \
;         acc[ai][bj][m][n] = __builtin_amdgcn_mfma_f32_16x16x32_bf16(Bt[n][k], At[m][k], acc[ai][bj][m][n], 0, 0, 0); __builtin_amdgcn_s_setprio(0); } while (0)
; template <class Epi, class Sched, bool ALIGN_EPI = false, bool SP2 = false>
; __device__ __forceinline__ void gemm_phase(PG8_LAS unsigned char* lds, const Gemm g, const Sched& S, const Epi& E) {
;     ...
;             PG8_LDB(B0, 0, 0); PG8_LDB(B1, 0, 1); PG8_SCHED; PG8_LDA(At, 0, 0); PG8_STAGE(PG8_SA(1, 1), a1 + hstep, voffA);
;             PG8_WAIT_V(8); PG8_WAIT_L(0); PG8_BAR; PG8_MMA(0, 0, At, B0); PG8_MMA(0, 1, At, B1); PG8_BAR; PG8_SCHED;
;             PG8_LDA(At, 0, 1); PG8_STAGE(PG8_SB(0, 0), b2, voffB); PG8_STAGE(PG8_SB(0, 1), b2 + hstep, voffB); PG8_STAGE(PG8_SA(0, 0), a2, voffA);
;             PG8_WAIT_V(8); PG8_WAIT_L(0); PG8_BAR; PG8_MMA(1, 0, At, B0); PG8_MMA(1, 1, At, B1); PG8_BAR; PG8_SCHED;
;             PG8_LDB(B0, 1, 0); PG8_LDB(B1, 1, 1); PG8_SCHED; PG8_LDA(At, 1, 0); PG8_STAGE(PG8_SA(0, 1), a2 + hstep, voffA);
;             PG8_WAIT_V(8); PG8_WAIT_L(0); PG8_BAR; PG8_MMA(0, 0, At, B0); PG8_MMA(0, 1, At, B1); PG8_BAR; PG8_SCHED;
;             PG8_LDA(At, 1, 1); PG8_STAGE(PG8_SB(1, 0), b3, voffB); PG8_STAGE(PG8_SB(1, 1), b3 + hstep, voffB); PG8_STAGE(PG8_SA(1, 0), a3, voffA);
;             PG8_WAIT_V(8); PG8_WAIT_L(0); PG8_BAR; PG8_MMA(1, 0, At, B0); PG8_MMA(1, 1, At, B1); PG8_BAR; PG8_SCHED;
.LBB0_698:
	ds_read_b128 v[134:137], v145
	ds_read_b128 v[152:155], v145 offset:1024
	ds_read_b128 v[156:159], v145 offset:2048
	ds_read_b128 v[160:163], v145 offset:3072
	ds_read_b128 v[164:167], v146
	ds_read_b128 v[168:171], v146 offset:1024
	ds_read_b128 v[172:175], v146 offset:2048
	ds_read_b128 v[176:179], v146 offset:3072
	s_cmp_eq_u32 s69, 60
	s_cselect_b32 s48, s41, s53
	s_cselect_b32 s49, s19, s58
	s_cselect_b32 s46, s52, s59
	s_cselect_b32 s47, s17, s68
	s_add_u32 s44, s48, 0x80
	s_addc_u32 s45, s49, 0
	ds_read_b128 v[180:183], v147
	ds_read_b128 v[184:187], v147 offset:1024
	ds_read_b128 v[188:191], v147 offset:2048
	ds_read_b128 v[192:195], v147 offset:3072
	ds_read_b128 v[196:199], v147 offset:4096
	ds_read_b128 v[200:203], v147 offset:5120
	ds_read_b128 v[204:207], v147 offset:6144
	ds_read_b128 v[208:211], v147 offset:7168
	s_mov_b32 m0, s67
	s_nop 0
	global_load_lds_dwordx4 v1, s[42:43]
	s_nop 0
	s_mov_b32 m0, s74
	s_nop 0
	global_load_lds_dwordx4 v141, s[42:43]
	s_nop 0
	s_waitcnt vmcnt(8)
	s_waitcnt lgkmcnt(0)
	s_barrier
	s_setprio 1
	s_waitcnt lgkmcnt(7)
	v_mfma_f32_16x16x32_bf16 v[126:129], v[134:137], v[180:183], v[126:129]
	v_mfma_f32_16x16x32_bf16 v[126:129], v[152:155], v[184:187], v[126:129]
	v_mfma_f32_16x16x32_bf16 v[122:125], v[160:163], v[184:187], v[122:125]
	v_mfma_f32_16x16x32_bf16 v[122:125], v[156:159], v[180:183], v[122:125]
	v_mfma_f32_16x16x32_bf16 v[118:121], v[164:167], v[180:183], v[118:121]
	v_mfma_f32_16x16x32_bf16 v[118:121], v[168:171], v[184:187], v[118:121]
	v_mfma_f32_16x16x32_bf16 v[114:117], v[176:179], v[184:187], v[114:117]
	v_mfma_f32_16x16x32_bf16 v[114:117], v[172:175], v[180:183], v[114:117]
	v_mfma_f32_16x16x32_bf16 v[98:101], v[172:175], v[188:191], v[98:101]
	v_mfma_f32_16x16x32_bf16 v[98:101], v[176:179], v[192:195], v[98:101]
	v_mfma_f32_16x16x32_bf16 v[102:105], v[168:171], v[192:195], v[102:105]
	v_mfma_f32_16x16x32_bf16 v[102:105], v[164:167], v[188:191], v[102:105]
	v_mfma_f32_16x16x32_bf16 v[106:109], v[156:159], v[188:191], v[106:109]
	v_mfma_f32_16x16x32_bf16 v[106:109], v[160:163], v[192:195], v[106:109]
	v_mfma_f32_16x16x32_bf16 v[110:113], v[152:155], v[192:195], v[110:113]
	v_mfma_f32_16x16x32_bf16 v[110:113], v[134:137], v[188:191], v[110:113]
	v_mfma_f32_16x16x32_bf16 v[94:97], v[134:137], v[196:199], v[94:97]
	v_mfma_f32_16x16x32_bf16 v[94:97], v[152:155], v[200:203], v[94:97]
	v_mfma_f32_16x16x32_bf16 v[90:93], v[160:163], v[200:203], v[90:93]
	v_mfma_f32_16x16x32_bf16 v[90:93], v[156:159], v[196:199], v[90:93]
	v_mfma_f32_16x16x32_bf16 v[86:89], v[164:167], v[196:199], v[86:89]
	v_mfma_f32_16x16x32_bf16 v[86:89], v[168:171], v[200:203], v[86:89]
	v_mfma_f32_16x16x32_bf16 v[82:85], v[176:179], v[200:203], v[82:85]
	v_mfma_f32_16x16x32_bf16 v[82:85], v[172:175], v[196:199], v[82:85]
	v_mfma_f32_16x16x32_bf16 v[66:69], v[172:175], v[204:207], v[66:69]
	v_mfma_f32_16x16x32_bf16 v[66:69], v[176:179], v[208:211], v[66:69]
	v_mfma_f32_16x16x32_bf16 v[70:73], v[168:171], v[208:211], v[70:73]
	v_mfma_f32_16x16x32_bf16 v[70:73], v[164:167], v[204:207], v[70:73]
	v_mfma_f32_16x16x32_bf16 v[74:77], v[156:159], v[204:207], v[74:77]
	v_mfma_f32_16x16x32_bf16 v[74:77], v[160:163], v[208:211], v[74:77]
	v_mfma_f32_16x16x32_bf16 v[78:81], v[152:155], v[208:211], v[78:81]
	s_setprio 2
	s_barrier
	v_mfma_f32_16x16x32_bf16 v[78:81], v[134:137], v[204:207], v[78:81]
	s_setprio 0
	ds_read_b128 v[180:183], v147 offset:16384
	ds_read_b128 v[184:187], v147 offset:17408
	ds_read_b128 v[188:191], v147 offset:18432
	ds_read_b128 v[192:195], v147 offset:19456
	ds_read_b128 v[196:199], v147 offset:20480
	ds_read_b128 v[200:203], v147 offset:21504
	ds_read_b128 v[252:255], v147 offset:22528
	ds_read_b128 v[208:211], v147 offset:23552
	s_mov_b32 m0, s35
	s_nop 0
	global_load_lds_dwordx4 v140, s[46:47]
	s_add_u32 s70, s46, 0x100000
	s_mov_b32 m0, s50
	s_nop 0
	global_load_lds_dwordx4 v142, s[46:47]
	s_addc_u32 s71, s47, 0
	s_mov_b32 m0, s51
	s_nop 0
	global_load_lds_dwordx4 v140, s[70:71]
	s_nop 0
	s_mov_b32 m0, s54
	s_nop 0
	global_load_lds_dwordx4 v142, s[70:71]
	s_nop 0
	s_mov_b32 m0, s3
	s_nop 0
	global_load_lds_dwordx4 v1, s[48:49]
	s_nop 0
	s_mov_b32 m0, s55
	s_nop 0
	global_load_lds_dwordx4 v141, s[48:49]
	s_waitcnt vmcnt(8)
	s_waitcnt lgkmcnt(0)
	s_barrier
	s_setprio 1
	s_waitcnt lgkmcnt(7)
	v_mfma_f32_16x16x32_bf16 v[62:65], v[134:137], v[180:183], v[62:65]
	v_mfma_f32_16x16x32_bf16 v[62:65], v[152:155], v[184:187], v[62:65]
	v_mfma_f32_16x16x32_bf16 v[58:61], v[160:163], v[184:187], v[58:61]
	v_mfma_f32_16x16x32_bf16 v[58:61], v[156:159], v[180:183], v[58:61]
	v_mfma_f32_16x16x32_bf16 v[54:57], v[164:167], v[180:183], v[54:57]
	v_mfma_f32_16x16x32_bf16 v[54:57], v[168:171], v[184:187], v[54:57]
	v_mfma_f32_16x16x32_bf16 v[50:53], v[176:179], v[184:187], v[50:53]
	v_mfma_f32_16x16x32_bf16 v[50:53], v[172:175], v[180:183], v[50:53]
	v_mfma_f32_16x16x32_bf16 v[34:37], v[172:175], v[188:191], v[34:37]
	v_mfma_f32_16x16x32_bf16 v[34:37], v[176:179], v[192:195], v[34:37]
	v_mfma_f32_16x16x32_bf16 v[38:41], v[168:171], v[192:195], v[38:41]
	v_mfma_f32_16x16x32_bf16 v[38:41], v[164:167], v[188:191], v[38:41]
	v_mfma_f32_16x16x32_bf16 v[42:45], v[156:159], v[188:191], v[42:45]
	v_mfma_f32_16x16x32_bf16 v[42:45], v[160:163], v[192:195], v[42:45]
	v_mfma_f32_16x16x32_bf16 v[46:49], v[152:155], v[192:195], v[46:49]
	v_mfma_f32_16x16x32_bf16 v[46:49], v[134:137], v[188:191], v[46:49]
	v_mfma_f32_16x16x32_bf16 v[30:33], v[134:137], v[196:199], v[30:33]
	v_mfma_f32_16x16x32_bf16 v[30:33], v[152:155], v[200:203], v[30:33]
	v_mfma_f32_16x16x32_bf16 v[26:29], v[160:163], v[200:203], v[26:29]
	v_mfma_f32_16x16x32_bf16 v[26:29], v[156:159], v[196:199], v[26:29]
	v_mfma_f32_16x16x32_bf16 v[22:25], v[164:167], v[196:199], v[22:25]
	v_mfma_f32_16x16x32_bf16 v[22:25], v[168:171], v[200:203], v[22:25]
	v_mfma_f32_16x16x32_bf16 v[18:21], v[176:179], v[200:203], v[18:21]
	v_mfma_f32_16x16x32_bf16 v[18:21], v[172:175], v[196:199], v[18:21]
	v_mfma_f32_16x16x32_bf16 v[2:5], v[172:175], v[252:255], v[2:5]
	v_mfma_f32_16x16x32_bf16 v[2:5], v[176:179], v[208:211], v[2:5]
	v_mfma_f32_16x16x32_bf16 v[6:9], v[168:171], v[208:211], v[6:9]
	v_mfma_f32_16x16x32_bf16 v[6:9], v[164:167], v[252:255], v[6:9]
	v_mfma_f32_16x16x32_bf16 v[10:13], v[156:159], v[252:255], v[10:13]
	v_mfma_f32_16x16x32_bf16 v[10:13], v[160:163], v[208:211], v[10:13]
	v_mfma_f32_16x16x32_bf16 v[14:17], v[152:155], v[208:211], v[14:17]
	s_setprio 2
	s_barrier
; #define PG8_STAGE(bufoff, gbase, voff) do { _Pragma("unroll") for (int _i = 0; _i < 2; ++_i) \
;         asm volatile("s_mov_b32 m0, %2\n\ts_nop 0\n\tglobal_load_lds_dwordx4 %0, %1" :: "v"((voff)[_i]), "s"((const char*)(gbase)), "s"(ldsbase + (unsigned)(bufoff) + ldsw + (unsigned)_i * 8192u) : "memory", "m0"); } while (0)
; #define PG8_LDA(dst, b, h) do { _Pragma("unroll") for (int m = 0; m < 4; ++m) _Pragma("unroll") for (int k = 0; k < 2; ++k) dst[m][k] = *(const PG8_LAS bf16x8*)(lds + PG8_SA(b, h) + aoff + m * 2048 + k * 1024); } while (0)
; #define PG8_LDB(dst, b, h) do { _Pragma("unroll") for (int n = 0; n < 2; ++n) _Pragma("unroll") for (int k = 0; k < 2; ++k) dst[n][k] = *(const PG8_LAS bf16x8*)(lds + PG8_SB(b, h) + boff + n * 2048 + k * 1024); } while (0)
; #define PG8_MMA(ai, bj, At, Bt) do { __builtin_amdgcn_s_setprio(1); _Pragma("unroll") for (int m = 0; m < 4; ++m) _Pragma("unroll") for (int n = 0; n < 2; ++n) _Pragma("unroll") for (int k = 0; k < 2; ++k) \
;         acc[ai][bj][m][n] = __builtin_amdgcn_mfma_f32_16x16x32_bf16(Bt[n][k], At[m][k], acc[ai][bj][m][n], 0, 0, 0); __builtin_amdgcn_s_setprio(0); } while (0)
; #define PG8_WAIT_V(n) asm volatile("s_waitcnt vmcnt(" #n ")" ::: "memory")
; #define PG8_WAIT_L(n) asm volatile("s_waitcnt lgkmcnt(" #n ")" ::: "memory")
; #define PG8_BAR __builtin_amdgcn_s_barrier()
; #define PG8_SCHED __builtin_amdgcn_sched_barrier(0)
; template <class Epi, class Sched, bool ALIGN_EPI = false, bool SP2 = false>
; __device__ __forceinline__ void gemm_phase(PG8_LAS unsigned char* lds, const Gemm g, const Sched& S, const Epi& E) {
;     ...
;         for (int t = 0; t < nt; t += 2) {
;             const bool last = (t == nt - 2);
;     ...
;             PG8_LDB(B0, 1, 0); PG8_LDB(B1, 1, 1); PG8_SCHED; PG8_LDA(At, 1, 0); PG8_STAGE(PG8_SA(0, 1), a2 + hstep, voffA);
;             PG8_WAIT_V(8); PG8_WAIT_L(0); PG8_BAR; PG8_MMA(0, 0, At, B0); PG8_MMA(0, 1, At, B1); PG8_BAR; PG8_SCHED;
;             PG8_LDA(At, 1, 1); PG8_STAGE(PG8_SB(1, 0), b3, voffB); PG8_STAGE(PG8_SB(1, 1), b3 + hstep, voffB); PG8_STAGE(PG8_SA(1, 0), a3, voffA);
;             PG8_WAIT_V(8); PG8_WAIT_L(0); PG8_BAR; PG8_MMA(1, 0, At, B0); PG8_MMA(1, 1, At, B1); PG8_BAR; PG8_SCHED;
	v_mfma_f32_16x16x32_bf16 v[14:17], v[134:137], v[252:255], v[14:17]
	s_setprio 0
	ds_read_b128 v[248:251], v148
	ds_read_b128 v[152:155], v148 offset:1024
	ds_read_b128 v[156:159], v148 offset:2048
	ds_read_b128 v[160:163], v148 offset:3072
	ds_read_b128 v[164:167], v149
	ds_read_b128 v[168:171], v149 offset:1024
	ds_read_b128 v[172:175], v149 offset:2048
	ds_read_b128 v[176:179], v149 offset:3072
	ds_read_b128 v[180:183], v147 offset:32768
	ds_read_b128 v[184:187], v147 offset:33792
	ds_read_b128 v[188:191], v147 offset:34816
	ds_read_b128 v[192:195], v147 offset:35840
	ds_read_b128 v[196:199], v147 offset:36864
	ds_read_b128 v[200:203], v147 offset:37888
	ds_read_b128 v[204:207], v147 offset:38912
	ds_read_b128 v[208:211], v147 offset:39936
	s_add_u32 s48, s48, 0x100000
	s_addc_u32 s49, s49, 0
	s_mov_b32 m0, s56
	s_nop 0
	global_load_lds_dwordx4 v1, s[48:49]
	s_nop 0
	s_mov_b32 m0, s57
	s_nop 0
	global_load_lds_dwordx4 v141, s[48:49]
	s_waitcnt vmcnt(8)
	s_waitcnt lgkmcnt(0)
	s_barrier
	s_setprio 1
	s_waitcnt lgkmcnt(7)
	v_mfma_f32_16x16x32_bf16 v[126:129], v[248:251], v[180:183], v[126:129]
	v_mfma_f32_16x16x32_bf16 v[126:129], v[152:155], v[184:187], v[126:129]
	v_mfma_f32_16x16x32_bf16 v[122:125], v[160:163], v[184:187], v[122:125]
	v_mfma_f32_16x16x32_bf16 v[122:125], v[156:159], v[180:183], v[122:125]
	v_mfma_f32_16x16x32_bf16 v[118:121], v[164:167], v[180:183], v[118:121]
	v_mfma_f32_16x16x32_bf16 v[118:121], v[168:171], v[184:187], v[118:121]
	v_mfma_f32_16x16x32_bf16 v[114:117], v[176:179], v[184:187], v[114:117]
	v_mfma_f32_16x16x32_bf16 v[114:117], v[172:175], v[180:183], v[114:117]
	v_mfma_f32_16x16x32_bf16 v[98:101], v[172:175], v[188:191], v[98:101]
	v_mfma_f32_16x16x32_bf16 v[98:101], v[176:179], v[192:195], v[98:101]
	v_mfma_f32_16x16x32_bf16 v[102:105], v[168:171], v[192:195], v[102:105]
	v_mfma_f32_16x16x32_bf16 v[102:105], v[164:167], v[188:191], v[102:105]
	v_mfma_f32_16x16x32_bf16 v[106:109], v[156:159], v[188:191], v[106:109]
	v_mfma_f32_16x16x32_bf16 v[106:109], v[160:163], v[192:195], v[106:109]
	v_mfma_f32_16x16x32_bf16 v[110:113], v[152:155], v[192:195], v[110:113]
	v_mfma_f32_16x16x32_bf16 v[110:113], v[248:251], v[188:191], v[110:113]
	v_mfma_f32_16x16x32_bf16 v[94:97], v[248:251], v[196:199], v[94:97]
	v_mfma_f32_16x16x32_bf16 v[94:97], v[152:155], v[200:203], v[94:97]
	v_mfma_f32_16x16x32_bf16 v[90:93], v[160:163], v[200:203], v[90:93]
	v_mfma_f32_16x16x32_bf16 v[90:93], v[156:159], v[196:199], v[90:93]
	v_mfma_f32_16x16x32_bf16 v[86:89], v[164:167], v[196:199], v[86:89]
	v_mfma_f32_16x16x32_bf16 v[86:89], v[168:171], v[200:203], v[86:89]
	v_mfma_f32_16x16x32_bf16 v[82:85], v[176:179], v[200:203], v[82:85]
	v_mfma_f32_16x16x32_bf16 v[82:85], v[172:175], v[196:199], v[82:85]
	v_mfma_f32_16x16x32_bf16 v[66:69], v[172:175], v[204:207], v[66:69]
	v_mfma_f32_16x16x32_bf16 v[66:69], v[176:179], v[208:211], v[66:69]
	v_mfma_f32_16x16x32_bf16 v[70:73], v[168:171], v[208:211], v[70:73]
	v_mfma_f32_16x16x32_bf16 v[70:73], v[164:167], v[204:207], v[70:73]
	v_mfma_f32_16x16x32_bf16 v[74:77], v[156:159], v[204:207], v[74:77]
	v_mfma_f32_16x16x32_bf16 v[74:77], v[160:163], v[208:211], v[74:77]
	v_mfma_f32_16x16x32_bf16 v[78:81], v[152:155], v[208:211], v[78:81]
	s_setprio 2
	s_barrier
	v_mfma_f32_16x16x32_bf16 v[78:81], v[248:251], v[204:207], v[78:81]
	s_setprio 0
	ds_read_b128 v[180:183], v147 offset:49152
	ds_read_b128 v[184:187], v147 offset:50176
	ds_read_b128 v[188:191], v147 offset:51200
	ds_read_b128 v[192:195], v147 offset:52224
	ds_read_b128 v[196:199], v147 offset:53248
	ds_read_b128 v[200:203], v147 offset:54272
	ds_read_b128 v[252:255], v147 offset:55296
	ds_read_b128 v[208:211], v147 offset:56320
	s_add_u32 s48, s46, 0x80
	s_addc_u32 s49, s47, 0
	s_mov_b32 m0, s61
	s_nop 0
	global_load_lds_dwordx4 v140, s[48:49]
	s_add_u32 s46, s46, 0x100080
	s_mov_b32 m0, s62
	s_nop 0
	global_load_lds_dwordx4 v142, s[48:49]
	s_addc_u32 s47, s47, 0
	s_mov_b32 m0, s65
	s_nop 0
	global_load_lds_dwordx4 v140, s[46:47]
	s_nop 0
	s_mov_b32 m0, s66
	s_nop 0
	global_load_lds_dwordx4 v142, s[46:47]
	s_nop 0
	s_mov_b32 m0, s63
	s_nop 0
	global_load_lds_dwordx4 v1, s[44:45]
	s_nop 0
	s_mov_b32 m0, s64
	s_nop 0
	global_load_lds_dwordx4 v141, s[44:45]
	s_nop 0
	s_waitcnt vmcnt(8)
	s_waitcnt lgkmcnt(0)
	s_barrier
	s_setprio 1
	s_waitcnt lgkmcnt(7)
	v_mfma_f32_16x16x32_bf16 v[62:65], v[248:251], v[180:183], v[62:65]
	v_mfma_f32_16x16x32_bf16 v[62:65], v[152:155], v[184:187], v[62:65]
	v_mfma_f32_16x16x32_bf16 v[58:61], v[160:163], v[184:187], v[58:61]
	v_mfma_f32_16x16x32_bf16 v[58:61], v[156:159], v[180:183], v[58:61]
	v_mfma_f32_16x16x32_bf16 v[54:57], v[164:167], v[180:183], v[54:57]
	v_mfma_f32_16x16x32_bf16 v[54:57], v[168:171], v[184:187], v[54:57]
	v_mfma_f32_16x16x32_bf16 v[50:53], v[176:179], v[184:187], v[50:53]
	v_mfma_f32_16x16x32_bf16 v[50:53], v[172:175], v[180:183], v[50:53]
	v_mfma_f32_16x16x32_bf16 v[34:37], v[172:175], v[188:191], v[34:37]
	v_mfma_f32_16x16x32_bf16 v[34:37], v[176:179], v[192:195], v[34:37]
	v_mfma_f32_16x16x32_bf16 v[38:41], v[168:171], v[192:195], v[38:41]
	v_mfma_f32_16x16x32_bf16 v[38:41], v[164:167], v[188:191], v[38:41]
	v_mfma_f32_16x16x32_bf16 v[42:45], v[156:159], v[188:191], v[42:45]
	v_mfma_f32_16x16x32_bf16 v[42:45], v[160:163], v[192:195], v[42:45]
	v_mfma_f32_16x16x32_bf16 v[46:49], v[152:155], v[192:195], v[46:49]
	v_mfma_f32_16x16x32_bf16 v[46:49], v[248:251], v[188:191], v[46:49]
	v_mfma_f32_16x16x32_bf16 v[30:33], v[248:251], v[196:199], v[30:33]
	v_mfma_f32_16x16x32_bf16 v[30:33], v[152:155], v[200:203], v[30:33]
	v_mfma_f32_16x16x32_bf16 v[26:29], v[160:163], v[200:203], v[26:29]
	v_mfma_f32_16x16x32_bf16 v[26:29], v[156:159], v[196:199], v[26:29]
	v_mfma_f32_16x16x32_bf16 v[22:25], v[164:167], v[196:199], v[22:25]
	v_mfma_f32_16x16x32_bf16 v[22:25], v[168:171], v[200:203], v[22:25]
	v_mfma_f32_16x16x32_bf16 v[18:21], v[176:179], v[200:203], v[18:21]
	v_mfma_f32_16x16x32_bf16 v[18:21], v[172:175], v[196:199], v[18:21]
	v_mfma_f32_16x16x32_bf16 v[2:5], v[172:175], v[252:255], v[2:5]
	v_mfma_f32_16x16x32_bf16 v[2:5], v[176:179], v[208:211], v[2:5]
	v_mfma_f32_16x16x32_bf16 v[6:9], v[168:171], v[208:211], v[6:9]
	v_mfma_f32_16x16x32_bf16 v[6:9], v[164:167], v[252:255], v[6:9]
	v_mfma_f32_16x16x32_bf16 v[10:13], v[156:159], v[252:255], v[10:13]
	v_mfma_f32_16x16x32_bf16 v[10:13], v[160:163], v[208:211], v[10:13]
	v_mfma_f32_16x16x32_bf16 v[14:17], v[152:155], v[208:211], v[14:17]
	s_setprio 2
	s_barrier
	v_mfma_f32_16x16x32_bf16 v[14:17], v[248:251], v[252:255], v[14:17]
	s_setprio 0
	s_add_i32 s69, s69, 2
	s_add_u32 s53, s53, 0x100
	s_addc_u32 s58, s58, 0
	s_add_u32 s59, s59, 0x100
	s_addc_u32 s68, s68, 0
	s_add_u32 s42, s42, 0x100
	s_addc_u32 s43, s43, 0
	s_cmp_gt_u32 s69, 61
	s_cbranch_scc0 .LBB0_698
	s_and_b64 vcc, exec, s[14:15]
	s_cbranch_vccz .LBB0_701
	s_barrier

; #define PG8_STAGE(bufoff, gbase, voff) do { _Pragma("unroll") for (int _i = 0; _i < 2; ++_i) \
;         asm volatile("s_mov_b32 m0, %2\n\ts_nop 0\n\tglobal_load_lds_dwordx4 %0, %1" :: "v"((voff)[_i]), "s"((const char*)(gbase)), "s"(ldsbase + (unsigned)(bufoff) + ldsw + (unsigned)_i * 8192u) : "memory", "m0"); } while (0)
; #define PG8_LDA(dst, b, h) do { _Pragma("unroll") for (int m = 0; m < 4; ++m) _Pragma("unroll") for (int k = 0; k < 2; ++k) dst[m][k] = *(const PG8_LAS bf16x8*)(lds + PG8_SA(b, h) + aoff + m * 2048 + k * 1024); } while (0)
; #define PG8_LDB(dst, b, h) do { _Pragma("unroll") for (int n = 0; n < 2; ++n) _Pragma("unroll") for (int k = 0; k < 2; ++k) dst[n][k] = *(const PG8_LAS bf16x8*)(lds + PG8_SB(b, h) + boff + n * 2048 + k * 1024); } while (0)
; #define PG8_MMA(ai, bj, At, Bt) do { __builtin_amdgcn_s_setprio(1); _Pragma("unroll") for (int m = 0; m < 4; ++m) _Pragma("unroll") for (int n = 0; n < 2; ++n) _Pragma("unroll") for (int k = 0; k < 2; ++k) \
;         acc[ai][bj][m][n] = __builtin_amdgcn_mfma_f32_16x16x32_bf16(Bt[n][k], At[m][k], acc[ai][bj][m][n], 0, 0, 0); __builtin_amdgcn_s_setprio(0); } while (0)
; #define PG8_WAIT_V(n) asm volatile("s_waitcnt vmcnt(" #n ")" ::: "memory")
; #define PG8_WAIT_L(n) asm volatile("s_waitcnt lgkmcnt(" #n ")" ::: "memory")
; #define PG8_BAR __builtin_amdgcn_s_barrier()
; #define PG8_SCHED __builtin_amdgcn_sched_barrier(0)
; template <class Epi, class Sched, bool ALIGN_EPI = false, bool SP2 = false>
; __device__ __forceinline__ void gemm_phase(PG8_LAS unsigned char* lds, const Gemm g, const Sched& S, const Epi& E) {
;     ...
;             PG8_LDB(B0, 0, 0); PG8_LDB(B1, 0, 1); PG8_SCHED; PG8_LDA(At, 0, 0); PG8_STAGE(PG8_SA(1, 1), a1 + hstep, voffA);
;             PG8_WAIT_V(8); PG8_WAIT_L(0); PG8_BAR; PG8_MMA(0, 0, At, B0); PG8_MMA(0, 1, At, B1); PG8_BAR; PG8_SCHED;
;             PG8_LDA(At, 0, 1); PG8_STAGE(PG8_SB(0, 0), b2, voffB); PG8_STAGE(PG8_SB(0, 1), b2 + hstep, voffB); PG8_STAGE(PG8_SA(0, 0), a2, voffA);
;             PG8_WAIT_V(8); PG8_WAIT_L(0); PG8_BAR; PG8_MMA(1, 0, At, B0); PG8_MMA(1, 1, At, B1); PG8_BAR; PG8_SCHED;
.LBB0_789:
	v_add_u32_e32 v164, 0x10000, v149
	v_add_u32_e32 v180, 0x14000, v149
	s_add_u32 s8, s40, 0x100
	s_waitcnt lgkmcnt(0)
	ds_read_b128 v[152:155], v164
	ds_read_b128 v[156:159], v164 offset:1024
	ds_read_b128 v[160:163], v164 offset:2048
	ds_read_b128 v[164:167], v164 offset:3072
	ds_read_b128 v[168:171], v180
	ds_read_b128 v[172:175], v180 offset:1024
	ds_read_b128 v[176:179], v180 offset:2048
	ds_read_b128 v[180:183], v180 offset:3072
	s_addc_u32 s9, s41, 0
	s_and_b64 s[38:39], s[38:39], exec
	s_cselect_b32 s46, s59, s8
	s_cselect_b32 s47, s17, s9
	s_cselect_b32 s39, s15, s75
	s_cselect_b32 s38, s71, s74
	s_add_u32 s42, s46, 0x80
	s_addc_u32 s43, s47, 0
	s_add_u32 s44, s38, 0x80
	s_addc_u32 s45, s39, 0
	ds_read_b128 v[184:187], v150
	ds_read_b128 v[188:191], v150 offset:1024
	ds_read_b128 v[192:195], v150 offset:2048
	ds_read_b128 v[196:199], v150 offset:3072
	ds_read_b128 v[200:203], v150 offset:4096
	ds_read_b128 v[204:207], v150 offset:5120
	ds_read_b128 v[208:211], v150 offset:6144
	ds_read_b128 v[212:215], v150 offset:7168
	s_add_u32 s40, s40, 0x100080
	s_addc_u32 s41, s41, 0
	s_mov_b32 m0, s64
	s_nop 0
	global_load_lds_dwordx4 v139, s[40:41]
	s_nop 0
	s_mov_b32 m0, s65
	s_nop 0
	global_load_lds_dwordx4 v141, s[40:41]
	s_nop 0
	s_waitcnt vmcnt(8)
	s_waitcnt lgkmcnt(0)
	s_barrier
	s_setprio 1
	s_waitcnt lgkmcnt(7)
	v_mfma_f32_16x16x32_bf16 v[126:129], v[152:155], v[184:187], v[126:129]
	v_mfma_f32_16x16x32_bf16 v[126:129], v[156:159], v[188:191], v[126:129]
	v_mfma_f32_16x16x32_bf16 v[122:125], v[164:167], v[188:191], v[122:125]
	v_mfma_f32_16x16x32_bf16 v[122:125], v[160:163], v[184:187], v[122:125]
	v_mfma_f32_16x16x32_bf16 v[118:121], v[168:171], v[184:187], v[118:121]
	v_mfma_f32_16x16x32_bf16 v[118:121], v[172:175], v[188:191], v[118:121]
	v_mfma_f32_16x16x32_bf16 v[114:117], v[180:183], v[188:191], v[114:117]
	v_mfma_f32_16x16x32_bf16 v[114:117], v[176:179], v[184:187], v[114:117]
	v_mfma_f32_16x16x32_bf16 v[98:101], v[176:179], v[192:195], v[98:101]
	v_mfma_f32_16x16x32_bf16 v[98:101], v[180:183], v[196:199], v[98:101]
	v_mfma_f32_16x16x32_bf16 v[102:105], v[172:175], v[196:199], v[102:105]
	v_mfma_f32_16x16x32_bf16 v[102:105], v[168:171], v[192:195], v[102:105]
	v_mfma_f32_16x16x32_bf16 v[106:109], v[160:163], v[192:195], v[106:109]
	v_mfma_f32_16x16x32_bf16 v[106:109], v[164:167], v[196:199], v[106:109]
	v_mfma_f32_16x16x32_bf16 v[110:113], v[156:159], v[196:199], v[110:113]
	v_mfma_f32_16x16x32_bf16 v[110:113], v[152:155], v[192:195], v[110:113]
	v_mfma_f32_16x16x32_bf16 v[94:97], v[152:155], v[200:203], v[94:97]
	v_mfma_f32_16x16x32_bf16 v[94:97], v[156:159], v[204:207], v[94:97]
	v_mfma_f32_16x16x32_bf16 v[90:93], v[164:167], v[204:207], v[90:93]
	v_mfma_f32_16x16x32_bf16 v[90:93], v[160:163], v[200:203], v[90:93]
	v_mfma_f32_16x16x32_bf16 v[86:89], v[168:171], v[200:203], v[86:89]
	v_mfma_f32_16x16x32_bf16 v[86:89], v[172:175], v[204:207], v[86:89]
	v_mfma_f32_16x16x32_bf16 v[82:85], v[180:183], v[204:207], v[82:85]
	v_mfma_f32_16x16x32_bf16 v[82:85], v[176:179], v[200:203], v[82:85]
	v_mfma_f32_16x16x32_bf16 v[66:69], v[176:179], v[208:211], v[66:69]
	v_mfma_f32_16x16x32_bf16 v[66:69], v[180:183], v[212:215], v[66:69]
	v_mfma_f32_16x16x32_bf16 v[70:73], v[172:175], v[212:215], v[70:73]
	v_mfma_f32_16x16x32_bf16 v[70:73], v[168:171], v[208:211], v[70:73]
	v_mfma_f32_16x16x32_bf16 v[74:77], v[160:163], v[208:211], v[74:77]
	v_mfma_f32_16x16x32_bf16 v[74:77], v[164:167], v[212:215], v[74:77]
	v_mfma_f32_16x16x32_bf16 v[78:81], v[156:159], v[212:215], v[78:81]
	s_setprio 2
	s_barrier
	v_mfma_f32_16x16x32_bf16 v[78:81], v[152:155], v[208:211], v[78:81]
	s_setprio 0
	ds_read_b128 v[184:187], v150 offset:16384
	ds_read_b128 v[188:191], v150 offset:17408
	ds_read_b128 v[192:195], v150 offset:18432
	ds_read_b128 v[196:199], v150 offset:19456
	ds_read_b128 v[200:203], v150 offset:20480
	ds_read_b128 v[204:207], v150 offset:21504
	ds_read_b128 v[252:255], v150 offset:22528
	ds_read_b128 v[212:215], v150 offset:23552
	s_mov_b32 m0, s49
	s_nop 0
	global_load_lds_dwordx4 v140, s[38:39]
	s_add_u32 s40, s38, 0x100000
	s_mov_b32 m0, s50
	s_nop 0
	global_load_lds_dwordx4 v142, s[38:39]
	s_addc_u32 s41, s39, 0
	s_mov_b32 m0, s51
	s_nop 0
	global_load_lds_dwordx4 v140, s[40:41]
	s_nop 0
	s_mov_b32 m0, s52
	s_nop 0
	global_load_lds_dwordx4 v142, s[40:41]
	s_nop 0
	s_mov_b32 m0, s37
	s_nop 0
	global_load_lds_dwordx4 v139, s[46:47]
	s_nop 0
	s_mov_b32 m0, s53
	s_nop 0
	global_load_lds_dwordx4 v141, s[46:47]
	s_waitcnt vmcnt(8)
	s_waitcnt lgkmcnt(0)
	s_barrier
; #define PG8_STAGE(bufoff, gbase, voff) do { _Pragma("unroll") for (int _i = 0; _i < 2; ++_i) \
;         asm volatile("s_mov_b32 m0, %2\n\ts_nop 0\n\tglobal_load_lds_dwordx4 %0, %1" :: "v"((voff)[_i]), "s"((const char*)(gbase)), "s"(ldsbase + (unsigned)(bufoff) + ldsw + (unsigned)_i * 8192u) : "memory", "m0"); } while (0)
; #define PG8_LDA(dst, b, h) do { _Pragma("unroll") for (int m = 0; m < 4; ++m) _Pragma("unroll") for (int k = 0; k < 2; ++k) dst[m][k] = *(const PG8_LAS bf16x8*)(lds + PG8_SA(b, h) + aoff + m * 2048 + k * 1024); } while (0)
; #define PG8_LDB(dst, b, h) do { _Pragma("unroll") for (int n = 0; n < 2; ++n) _Pragma("unroll") for (int k = 0; k < 2; ++k) dst[n][k] = *(const PG8_LAS bf16x8*)(lds + PG8_SB(b, h) + boff + n * 2048 + k * 1024); } while (0)
; #define PG8_MMA(ai, bj, At, Bt) do { __builtin_amdgcn_s_setprio(1); _Pragma("unroll") for (int m = 0; m < 4; ++m) _Pragma("unroll") for (int n = 0; n < 2; ++n) _Pragma("unroll") for (int k = 0; k < 2; ++k) \
;         acc[ai][bj][m][n] = __builtin_amdgcn_mfma_f32_16x16x32_bf16(Bt[n][k], At[m][k], acc[ai][bj][m][n], 0, 0, 0); __builtin_amdgcn_s_setprio(0); } while (0)
; #define PG8_WAIT_V(n) asm volatile("s_waitcnt vmcnt(" #n ")" ::: "memory")
; #define PG8_WAIT_L(n) asm volatile("s_waitcnt lgkmcnt(" #n ")" ::: "memory")
; #define PG8_BAR __builtin_amdgcn_s_barrier()
; #define PG8_SCHED __builtin_amdgcn_sched_barrier(0)
; template <class Epi, class Sched, bool ALIGN_EPI = false, bool SP2 = false>
; __device__ __forceinline__ void gemm_phase(PG8_LAS unsigned char* lds, const Gemm g, const Sched& S, const Epi& E) {
;     ...
;             PG8_WAIT_V(8); PG8_WAIT_L(0); PG8_BAR; PG8_MMA(1, 0, At, B0); PG8_MMA(1, 1, At, B1); PG8_BAR; PG8_SCHED;
;             PG8_LDB(B0, 1, 0); PG8_LDB(B1, 1, 1); PG8_SCHED; PG8_LDA(At, 1, 0); PG8_STAGE(PG8_SA(0, 1), a2 + hstep, voffA);
;             PG8_WAIT_V(8); PG8_WAIT_L(0); PG8_BAR; PG8_MMA(0, 0, At, B0); PG8_MMA(0, 1, At, B1); PG8_BAR; PG8_SCHED;
;             PG8_LDA(At, 1, 1); PG8_STAGE(PG8_SB(1, 0), b3, voffB); PG8_STAGE(PG8_SB(1, 1), b3 + hstep, voffB); PG8_STAGE(PG8_SA(1, 0), a3, voffA);
;             PG8_WAIT_V(8); PG8_WAIT_L(0); PG8_BAR; PG8_MMA(1, 0, At, B0); PG8_MMA(1, 1, At, B1); PG8_BAR; PG8_SCHED;
	s_setprio 1
	s_waitcnt lgkmcnt(7)
	v_mfma_f32_16x16x32_bf16 v[62:65], v[152:155], v[184:187], v[62:65]
	v_mfma_f32_16x16x32_bf16 v[62:65], v[156:159], v[188:191], v[62:65]
	v_mfma_f32_16x16x32_bf16 v[58:61], v[164:167], v[188:191], v[58:61]
	v_mfma_f32_16x16x32_bf16 v[58:61], v[160:163], v[184:187], v[58:61]
	v_mfma_f32_16x16x32_bf16 v[54:57], v[168:171], v[184:187], v[54:57]
	v_mfma_f32_16x16x32_bf16 v[54:57], v[172:175], v[188:191], v[54:57]
	v_mfma_f32_16x16x32_bf16 v[50:53], v[180:183], v[188:191], v[50:53]
	v_mfma_f32_16x16x32_bf16 v[50:53], v[176:179], v[184:187], v[50:53]
	v_mfma_f32_16x16x32_bf16 v[34:37], v[176:179], v[192:195], v[34:37]
	v_mfma_f32_16x16x32_bf16 v[34:37], v[180:183], v[196:199], v[34:37]
	v_mfma_f32_16x16x32_bf16 v[38:41], v[172:175], v[196:199], v[38:41]
	v_mfma_f32_16x16x32_bf16 v[38:41], v[168:171], v[192:195], v[38:41]
	v_mfma_f32_16x16x32_bf16 v[42:45], v[160:163], v[192:195], v[42:45]
	v_mfma_f32_16x16x32_bf16 v[42:45], v[164:167], v[196:199], v[42:45]
	v_mfma_f32_16x16x32_bf16 v[46:49], v[156:159], v[196:199], v[46:49]
	v_mfma_f32_16x16x32_bf16 v[46:49], v[152:155], v[192:195], v[46:49]
	v_mfma_f32_16x16x32_bf16 v[30:33], v[152:155], v[200:203], v[30:33]
	v_mfma_f32_16x16x32_bf16 v[30:33], v[156:159], v[204:207], v[30:33]
	v_mfma_f32_16x16x32_bf16 v[26:29], v[164:167], v[204:207], v[26:29]
	v_mfma_f32_16x16x32_bf16 v[26:29], v[160:163], v[200:203], v[26:29]
	v_mfma_f32_16x16x32_bf16 v[22:25], v[168:171], v[200:203], v[22:25]
	v_mfma_f32_16x16x32_bf16 v[22:25], v[172:175], v[204:207], v[22:25]
	v_mfma_f32_16x16x32_bf16 v[18:21], v[180:183], v[204:207], v[18:21]
	v_mfma_f32_16x16x32_bf16 v[18:21], v[176:179], v[200:203], v[18:21]
	v_mfma_f32_16x16x32_bf16 v[2:5], v[176:179], v[252:255], v[2:5]
	v_mfma_f32_16x16x32_bf16 v[2:5], v[180:183], v[212:215], v[2:5]
	v_mfma_f32_16x16x32_bf16 v[6:9], v[172:175], v[212:215], v[6:9]
	v_mfma_f32_16x16x32_bf16 v[6:9], v[168:171], v[252:255], v[6:9]
	v_mfma_f32_16x16x32_bf16 v[10:13], v[160:163], v[252:255], v[10:13]
	v_mfma_f32_16x16x32_bf16 v[10:13], v[164:167], v[212:215], v[10:13]
	v_mfma_f32_16x16x32_bf16 v[14:17], v[156:159], v[212:215], v[14:17]
	s_setprio 2
	s_barrier
	v_mfma_f32_16x16x32_bf16 v[14:17], v[152:155], v[252:255], v[14:17]
	s_setprio 0
	v_add_u32_e32 v164, 0x18000, v149
	v_add_u32_e32 v180, 0x1c000, v149
	ds_read_b128 v[248:251], v164
	ds_read_b128 v[156:159], v164 offset:1024
	ds_read_b128 v[160:163], v164 offset:2048
	ds_read_b128 v[164:167], v164 offset:3072
	ds_read_b128 v[168:171], v180
	ds_read_b128 v[172:175], v180 offset:1024
	ds_read_b128 v[176:179], v180 offset:2048
	ds_read_b128 v[180:183], v180 offset:3072
	ds_read_b128 v[184:187], v150 offset:32768
	ds_read_b128 v[188:191], v150 offset:33792
	ds_read_b128 v[192:195], v150 offset:34816
	ds_read_b128 v[196:199], v150 offset:35840
	ds_read_b128 v[200:203], v150 offset:36864
	ds_read_b128 v[204:207], v150 offset:37888
	ds_read_b128 v[208:211], v150 offset:38912
	ds_read_b128 v[212:215], v150 offset:39936
	s_add_u32 s40, s46, 0x100000
	s_addc_u32 s41, s47, 0
	s_mov_b32 m0, s54
	s_nop 0
	global_load_lds_dwordx4 v139, s[40:41]
	s_nop 0
	s_mov_b32 m0, s55
	s_nop 0
	global_load_lds_dwordx4 v141, s[40:41]
	s_waitcnt vmcnt(8)
	s_waitcnt lgkmcnt(0)
	s_barrier
	s_setprio 1
	s_waitcnt lgkmcnt(7)
	v_mfma_f32_16x16x32_bf16 v[126:129], v[248:251], v[184:187], v[126:129]
	v_mfma_f32_16x16x32_bf16 v[126:129], v[156:159], v[188:191], v[126:129]
	v_mfma_f32_16x16x32_bf16 v[122:125], v[164:167], v[188:191], v[122:125]
	v_mfma_f32_16x16x32_bf16 v[122:125], v[160:163], v[184:187], v[122:125]
	v_mfma_f32_16x16x32_bf16 v[118:121], v[168:171], v[184:187], v[118:121]
	v_mfma_f32_16x16x32_bf16 v[118:121], v[172:175], v[188:191], v[118:121]
	v_mfma_f32_16x16x32_bf16 v[114:117], v[180:183], v[188:191], v[114:117]
	v_mfma_f32_16x16x32_bf16 v[114:117], v[176:179], v[184:187], v[114:117]
	v_mfma_f32_16x16x32_bf16 v[98:101], v[176:179], v[192:195], v[98:101]
	v_mfma_f32_16x16x32_bf16 v[98:101], v[180:183], v[196:199], v[98:101]
	v_mfma_f32_16x16x32_bf16 v[102:105], v[172:175], v[196:199], v[102:105]
	v_mfma_f32_16x16x32_bf16 v[102:105], v[168:171], v[192:195], v[102:105]
	v_mfma_f32_16x16x32_bf16 v[106:109], v[160:163], v[192:195], v[106:109]
	v_mfma_f32_16x16x32_bf16 v[106:109], v[164:167], v[196:199], v[106:109]
	v_mfma_f32_16x16x32_bf16 v[110:113], v[156:159], v[196:199], v[110:113]
	v_mfma_f32_16x16x32_bf16 v[110:113], v[248:251], v[192:195], v[110:113]
	v_mfma_f32_16x16x32_bf16 v[94:97], v[248:251], v[200:203], v[94:97]
	v_mfma_f32_16x16x32_bf16 v[94:97], v[156:159], v[204:207], v[94:97]
	v_mfma_f32_16x16x32_bf16 v[90:93], v[164:167], v[204:207], v[90:93]
	v_mfma_f32_16x16x32_bf16 v[90:93], v[160:163], v[200:203], v[90:93]
	v_mfma_f32_16x16x32_bf16 v[86:89], v[168:171], v[200:203], v[86:89]
	v_mfma_f32_16x16x32_bf16 v[86:89], v[172:175], v[204:207], v[86:89]
	v_mfma_f32_16x16x32_bf16 v[82:85], v[180:183], v[204:207], v[82:85]
	v_mfma_f32_16x16x32_bf16 v[82:85], v[176:179], v[200:203], v[82:85]
	v_mfma_f32_16x16x32_bf16 v[66:69], v[176:179], v[208:211], v[66:69]
	v_mfma_f32_16x16x32_bf16 v[66:69], v[180:183], v[212:215], v[66:69]
	v_mfma_f32_16x16x32_bf16 v[70:73], v[172:175], v[212:215], v[70:73]
	v_mfma_f32_16x16x32_bf16 v[70:73], v[168:171], v[208:211], v[70:73]
	v_mfma_f32_16x16x32_bf16 v[74:77], v[160:163], v[208:211], v[74:77]
	v_mfma_f32_16x16x32_bf16 v[74:77], v[164:167], v[212:215], v[74:77]
	v_mfma_f32_16x16x32_bf16 v[78:81], v[156:159], v[212:215], v[78:81]
	s_setprio 2
	s_barrier
; #define PG8_STAGE(bufoff, gbase, voff) do { _Pragma("unroll") for (int _i = 0; _i < 2; ++_i) \
;         asm volatile("s_mov_b32 m0, %2\n\ts_nop 0\n\tglobal_load_lds_dwordx4 %0, %1" :: "v"((voff)[_i]), "s"((const char*)(gbase)), "s"(ldsbase + (unsigned)(bufoff) + ldsw + (unsigned)_i * 8192u) : "memory", "m0"); } while (0)
; #define PG8_LDA(dst, b, h) do { _Pragma("unroll") for (int m = 0; m < 4; ++m) _Pragma("unroll") for (int k = 0; k < 2; ++k) dst[m][k] = *(const PG8_LAS bf16x8*)(lds + PG8_SA(b, h) + aoff + m * 2048 + k * 1024); } while (0)
; #define PG8_MMA(ai, bj, At, Bt) do { __builtin_amdgcn_s_setprio(1); _Pragma("unroll") for (int m = 0; m < 4; ++m) _Pragma("unroll") for (int n = 0; n < 2; ++n) _Pragma("unroll") for (int k = 0; k < 2; ++k) \
;         acc[ai][bj][m][n] = __builtin_amdgcn_mfma_f32_16x16x32_bf16(Bt[n][k], At[m][k], acc[ai][bj][m][n], 0, 0, 0); __builtin_amdgcn_s_setprio(0); } while (0)
; #define PG8_WAIT_V(n) asm volatile("s_waitcnt vmcnt(" #n ")" ::: "memory")
; #define PG8_WAIT_L(n) asm volatile("s_waitcnt lgkmcnt(" #n ")" ::: "memory")
; #define PG8_BAR __builtin_amdgcn_s_barrier()
; #define PG8_SCHED __builtin_amdgcn_sched_barrier(0)
; template <class Epi, class Sched, bool ALIGN_EPI = false, bool SP2 = false>
; __device__ __forceinline__ void gemm_phase(PG8_LAS unsigned char* lds, const Gemm g, const Sched& S, const Epi& E) {
;     ...
;         for (int t = 0; t < nt; t += 2) {
;             const bool last = (t == nt - 2);
;     ...
;             PG8_LDA(At, 1, 1); PG8_STAGE(PG8_SB(1, 0), b3, voffB); PG8_STAGE(PG8_SB(1, 1), b3 + hstep, voffB); PG8_STAGE(PG8_SA(1, 0), a3, voffA);
;             PG8_WAIT_V(8); PG8_WAIT_L(0); PG8_BAR; PG8_MMA(1, 0, At, B0); PG8_MMA(1, 1, At, B1); PG8_BAR; PG8_SCHED;
	v_mfma_f32_16x16x32_bf16 v[78:81], v[248:251], v[208:211], v[78:81]
	s_setprio 0
	ds_read_b128 v[184:187], v150 offset:49152
	ds_read_b128 v[188:191], v150 offset:50176
	ds_read_b128 v[192:195], v150 offset:51200
	ds_read_b128 v[196:199], v150 offset:52224
	ds_read_b128 v[200:203], v150 offset:53248
	ds_read_b128 v[204:207], v150 offset:54272
	ds_read_b128 v[252:255], v150 offset:55296
	ds_read_b128 v[212:215], v150 offset:56320
	s_mov_b32 m0, s56
	s_nop 0
	global_load_lds_dwordx4 v140, s[44:45]
	s_add_u32 s38, s38, 0x100080
	s_mov_b32 m0, s57
	s_nop 0
	global_load_lds_dwordx4 v142, s[44:45]
	s_addc_u32 s39, s39, 0
	s_mov_b32 m0, s62
	s_nop 0
	global_load_lds_dwordx4 v140, s[38:39]
	s_nop 0
	s_mov_b32 m0, s63
	s_nop 0
	global_load_lds_dwordx4 v142, s[38:39]
	s_nop 0
	s_mov_b32 m0, s60
	s_nop 0
	global_load_lds_dwordx4 v139, s[42:43]
	s_nop 0
	s_mov_b32 m0, s61
	s_nop 0
	global_load_lds_dwordx4 v141, s[42:43]
	s_waitcnt vmcnt(8)
	s_waitcnt lgkmcnt(0)
	s_barrier
	s_setprio 1
	s_waitcnt lgkmcnt(7)
	v_mfma_f32_16x16x32_bf16 v[62:65], v[248:251], v[184:187], v[62:65]
	v_mfma_f32_16x16x32_bf16 v[62:65], v[156:159], v[188:191], v[62:65]
	v_mfma_f32_16x16x32_bf16 v[58:61], v[164:167], v[188:191], v[58:61]
	v_mfma_f32_16x16x32_bf16 v[58:61], v[160:163], v[184:187], v[58:61]
	v_mfma_f32_16x16x32_bf16 v[54:57], v[168:171], v[184:187], v[54:57]
	v_mfma_f32_16x16x32_bf16 v[54:57], v[172:175], v[188:191], v[54:57]
	v_mfma_f32_16x16x32_bf16 v[50:53], v[180:183], v[188:191], v[50:53]
	v_mfma_f32_16x16x32_bf16 v[50:53], v[176:179], v[184:187], v[50:53]
	v_mfma_f32_16x16x32_bf16 v[34:37], v[176:179], v[192:195], v[34:37]
	v_mfma_f32_16x16x32_bf16 v[34:37], v[180:183], v[196:199], v[34:37]
	v_mfma_f32_16x16x32_bf16 v[38:41], v[172:175], v[196:199], v[38:41]
	v_mfma_f32_16x16x32_bf16 v[38:41], v[168:171], v[192:195], v[38:41]
	v_mfma_f32_16x16x32_bf16 v[42:45], v[160:163], v[192:195], v[42:45]
	v_mfma_f32_16x16x32_bf16 v[42:45], v[164:167], v[196:199], v[42:45]
	v_mfma_f32_16x16x32_bf16 v[46:49], v[156:159], v[196:199], v[46:49]
	v_mfma_f32_16x16x32_bf16 v[46:49], v[248:251], v[192:195], v[46:49]
	v_mfma_f32_16x16x32_bf16 v[30:33], v[248:251], v[200:203], v[30:33]
	v_mfma_f32_16x16x32_bf16 v[30:33], v[156:159], v[204:207], v[30:33]
	v_mfma_f32_16x16x32_bf16 v[26:29], v[164:167], v[204:207], v[26:29]
	v_mfma_f32_16x16x32_bf16 v[26:29], v[160:163], v[200:203], v[26:29]
	v_mfma_f32_16x16x32_bf16 v[22:25], v[168:171], v[200:203], v[22:25]
	v_mfma_f32_16x16x32_bf16 v[22:25], v[172:175], v[204:207], v[22:25]
	v_mfma_f32_16x16x32_bf16 v[18:21], v[180:183], v[204:207], v[18:21]
	v_mfma_f32_16x16x32_bf16 v[18:21], v[176:179], v[200:203], v[18:21]
	v_mfma_f32_16x16x32_bf16 v[2:5], v[176:179], v[252:255], v[2:5]
	v_mfma_f32_16x16x32_bf16 v[2:5], v[180:183], v[212:215], v[2:5]
	v_mfma_f32_16x16x32_bf16 v[6:9], v[172:175], v[212:215], v[6:9]
	v_mfma_f32_16x16x32_bf16 v[6:9], v[168:171], v[252:255], v[6:9]
	v_mfma_f32_16x16x32_bf16 v[10:13], v[160:163], v[252:255], v[10:13]
	v_mfma_f32_16x16x32_bf16 v[10:13], v[164:167], v[212:215], v[10:13]
	v_mfma_f32_16x16x32_bf16 v[14:17], v[156:159], v[212:215], v[14:17]
	s_setprio 2
	s_barrier
	v_mfma_f32_16x16x32_bf16 v[14:17], v[248:251], v[252:255], v[14:17]
	s_setprio 0
	s_add_i32 s76, s76, 2
	s_add_u32 s74, s74, 0x100
	s_addc_u32 s75, s75, 0
	s_cmp_gt_u32 s76, 61
	s_cbranch_scc1 .LBB0_780
	s_mov_b64 s[40:41], s[8:9]
	s_branch .LBB0_784
